# combined: log1p via compensated v_log, LRU activation-row L2 prefetch, carry phase software-pipelined
# speedup vs baseline: 1.0044x; 1.0044x over previous
; #define LAS __attribute__((address_space(3)))
; template <int MODE>
; __device__ __forceinline__ void lru_unit(const Args& a, int l, int b, int ch, LAS unsigned char* lds) {
;     int tid_ = threadIdx.x; asm volatile("" : "+v"(tid_));
;     const int tid = tid_, w = __builtin_amdgcn_readfirstlane(tid >> 6), lane = tid & 63, r32 = lane & 31, h = lane >> 5;
;     const int c = w * 64 + lane, t0 = ch * 32;
;     const bf16* proj = (const bf16*)(a.ws + WS_PROJ);
;     LAS unsigned char* xcb = lds + w * 12800;
;     LAS float* au = (LAS float*)(lds + w * 12800 + 4608);
;     const float* cw = a.in[7] + (size_t)l * 4 * LW;
;     const float cw0 = cw[c], cw1 = cw[LW + c], cw2 = cw[2 * LW + c], cw3 = cw[3 * LW + c], cb = a.in[8][l * LW + c];
;     float prm[2][2][3];
; #pragma unroll
;     for (int d = 0; d < 2; ++d)
; #pragma unroll
;         for (int nt = 0; nt < 2; ++nt) { const int cc = (l * 2 + d) * LW + w * 64 + nt * 32 + r32;
;             prm[d][nt][0] = a.in[10][cc]; prm[d][nt][1] = a.in[12][cc]; prm[d][nt][2] = a.in[13][cc]; }
;     const bf16* xp = proj + (size_t)b * SEQ * DIN + c;
;     float xin[35], gl[32];
;     unsigned short xraw[35], graw[32];
; #pragma unroll
;     for (int i = 0; i < 35; ++i) { const int t = t0 - 2 + i, tc = t < 0 ? 0 : (t >= SEQ ? SEQ - 1 : t); xraw[i] = xp[(size_t)tc * DIN]; }
;     if (MODE == 1) {
; #pragma unroll
;         for (int t = 0; t < 32; ++t) graw[t] = xp[(size_t)(t0 + t) * DIN + LW];
.LBB0_180:
	s_cmpk_gt_i32 s65, 0xff
	s_mov_b64 s[0:1], -1
	s_barrier
	s_cbranch_scc0 .LBB0_182
	s_add_i32 s0, s65, 0xffffff00
	s_lshr_b32 s40, s0, 7
	s_mul_i32 s88, s40, 0x700000
	s_and_b32 s28, s65, 0x7f
	s_lshl_b32 s29, s28, 5
	s_lshl_b64 s[0:1], s[88:89], 1
	s_add_u32 s38, s24, s0
	s_addc_u32 s39, s25, s1
	s_lshl_b32 s0, s40, 21
	s_lshl_b32 s1, s28, 14
	s_or_b32 s88, s0, s1
	s_min_u32 s41, s29, 0xfdf
	s_lshl_b64 s[0:1], s[88:89], 2
	s_add_u32 s44, s72, s0
	s_addc_u32 s45, s73, s1
	s_add_u32 s46, s50, s0
	s_addc_u32 s47, s51, s1
	s_lshl_b32 s0, s40, 17
	s_lshl_b32 s1, s28, 10
	s_or_b32 s88, s0, s1
	s_lshl_b64 s[0:1], s[88:89], 3
	s_add_u32 s42, s74, s0
	s_addc_u32 s43, s75, s1
	v_mov_b32_e32 v66, v226
	s_add_u32 s40, s50, s0
	s_movk_i32 s59, 0xffc0
	v_readfirstlane_b32 s0, v66
	s_mul_i32 s88, s28, 0x1c000
	s_mov_b32 s4, 0x1c000
	v_mov_b32_e32 v0, s0
	v_bfi_b32 v82, s59, v0, v66
	v_ashrrev_i32_e32 v83, 31, v82
	v_lshl_add_u64 v[36:37], v[82:83], 1, s[38:39]
	v_lshl_add_u64 v[4:5], v[36:37], 0, s[88:89]
	v_mov_b32_e32 v214, 0x1c00
	v_mov_b32_e32 v215, 0
	v_mov_b32_e32 v212, v4
	v_mov_b32_e32 v213, v5
	global_load_ushort v210, v[212:213], off
	global_load_ushort v210, v[212:213], off offset:3584
	v_lshl_add_u64 v[212:213], v[212:213], 0, v[214:215]
	global_load_ushort v210, v[212:213], off
	global_load_ushort v210, v[212:213], off offset:3584
	v_lshl_add_u64 v[212:213], v[212:213], 0, v[214:215]
	global_load_ushort v210, v[212:213], off
	global_load_ushort v210, v[212:213], off offset:3584
	v_lshl_add_u64 v[212:213], v[212:213], 0, v[214:215]
	global_load_ushort v210, v[212:213], off
	global_load_ushort v210, v[212:213], off offset:3584
	v_lshl_add_u64 v[212:213], v[212:213], 0, v[214:215]
	global_load_ushort v210, v[212:213], off
	global_load_ushort v210, v[212:213], off offset:3584
	v_lshl_add_u64 v[212:213], v[212:213], 0, v[214:215]
	global_load_ushort v210, v[212:213], off
	global_load_ushort v210, v[212:213], off offset:3584
	v_lshl_add_u64 v[212:213], v[212:213], 0, v[214:215]
	global_load_ushort v210, v[212:213], off
	global_load_ushort v210, v[212:213], off offset:3584
	v_lshl_add_u64 v[212:213], v[212:213], 0, v[214:215]
	global_load_ushort v210, v[212:213], off
	global_load_ushort v210, v[212:213], off offset:3584
	v_lshl_add_u64 v[212:213], v[212:213], 0, v[214:215]
	global_load_ushort v210, v[212:213], off
	global_load_ushort v210, v[212:213], off offset:3584
	v_lshl_add_u64 v[212:213], v[212:213], 0, v[214:215]
	global_load_ushort v210, v[212:213], off
	global_load_ushort v210, v[212:213], off offset:3584
	v_lshl_add_u64 v[212:213], v[212:213], 0, v[214:215]
	global_load_ushort v210, v[212:213], off
	global_load_ushort v210, v[212:213], off offset:3584
	v_lshl_add_u64 v[212:213], v[212:213], 0, v[214:215]
	global_load_ushort v210, v[212:213], off
	global_load_ushort v210, v[212:213], off offset:3584
	v_lshl_add_u64 v[212:213], v[212:213], 0, v[214:215]
	global_load_ushort v210, v[212:213], off
	global_load_ushort v210, v[212:213], off offset:3584
	v_lshl_add_u64 v[212:213], v[212:213], 0, v[214:215]
	global_load_ushort v210, v[212:213], off
	global_load_ushort v210, v[212:213], off offset:3584
	v_lshl_add_u64 v[212:213], v[212:213], 0, v[214:215]
	global_load_ushort v210, v[212:213], off
	global_load_ushort v210, v[212:213], off offset:3584
	v_lshl_add_u64 v[212:213], v[212:213], 0, v[214:215]
	global_load_ushort v210, v[212:213], off
	global_load_ushort v210, v[212:213], off offset:3584
	v_lshl_add_u64 v[212:213], v[212:213], 0, v[214:215]
	s_mul_i32 s88, s41, 0xe00
	v_lshl_add_u64 v[2:3], v[36:37], 0, s[88:89]
	v_add_co_u32_e32 v2, vcc, s4, v2
	v_readlane_b32 s4, v254, 37
	s_nop 0
	v_addc_co_u32_e32 v3, vcc, 0, v3, vcc
	global_load_ushort v0, v[2:3], off
	v_lshlrev_b64 v[2:3], 2, v[82:83]
	v_readlane_b32 s5, v254, 38
	s_movk_i32 s61, 0x1000
	s_movk_i32 s59, 0x2000
	v_lshl_add_u64 v[24:25], s[4:5], 0, v[2:3]
	v_add_co_u32_e32 v26, vcc, s61, v24
	s_movk_i32 s60, 0x3000
	s_nop 0
	v_addc_co_u32_e32 v27, vcc, 0, v25, vcc
	v_add_co_u32_e32 v30, vcc, s61, v4
	s_addc_u32 s41, s51, s1
	s_nop 0
	v_addc_co_u32_e32 v31, vcc, 0, v5, vcc
	v_add_co_u32_e32 v28, vcc, s59, v4
	s_movk_i32 s1, 0x4000
	s_nop 0
	v_addc_co_u32_e32 v29, vcc, 0, v5, vcc
	v_add_co_u32_e32 v32, vcc, s60, v4
	v_and_b32_e32 v164, 31, v66
	s_nop 0
	v_addc_co_u32_e32 v33, vcc, 0, v5, vcc
	v_add_co_u32_e32 v22, vcc, s1, v4
	s_movk_i32 s1, 0x5000
	s_nop 0
	v_addc_co_u32_e32 v23, vcc, 0, v5, vcc
	v_add_co_u32_e32 v10, vcc, s1, v4
	s_movk_i32 s1, 0x6000
	s_nop 0
	v_addc_co_u32_e32 v11, vcc, 0, v5, vcc
	v_add_co_u32_e32 v20, vcc, s1, v4
	s_movk_i32 s1, 0x7000
	s_nop 0
	v_addc_co_u32_e32 v21, vcc, 0, v5, vcc
	v_add_co_u32_e32 v18, vcc, s1, v4
	s_mov_b32 s1, 0x8000
	s_nop 0
	v_addc_co_u32_e32 v19, vcc, 0, v5, vcc
	v_add_co_u32_e32 v12, vcc, s1, v4
	s_mov_b32 s1, 0x9000
	s_nop 0
	v_addc_co_u32_e32 v13, vcc, 0, v5, vcc
	v_add_co_u32_e32 v14, vcc, s1, v4
	s_mov_b32 s1, 0xa000
	s_nop 0
	v_addc_co_u32_e32 v15, vcc, 0, v5, vcc
	v_add_co_u32_e32 v16, vcc, s1, v4
	s_mov_b32 s1, 0xc000
	s_nop 0
	v_addc_co_u32_e32 v17, vcc, 0, v5, vcc
	v_add_co_u32_e32 v6, vcc, s90, v4
	v_readlane_b32 s4, v254, 39
	s_nop 0
	v_addc_co_u32_e32 v7, vcc, 0, v5, vcc
	v_add_co_u32_e32 v8, vcc, s1, v4
	s_and_b32 s1, s0, 0xffffffc0
	s_nop 0
	v_addc_co_u32_e32 v9, vcc, 0, v5, vcc
	s_cmpk_lg_i32 s28, 0x7f
	s_cselect_b64 vcc, -1, 0
	s_add_i32 s28, s29, -2
	s_max_i32 s38, s28, 0
	s_add_i32 s29, s29, -1
	s_mul_i32 s88, s38, 0xe00
	s_max_i32 s38, s29, 0
	v_lshl_add_u64 v[34:35], v[36:37], 0, s[88:89]
	s_mul_i32 s88, s38, 0xe00
	v_lshl_add_u64 v[36:37], v[36:37], 0, s[88:89]
	global_load_ushort v64, v[36:37], off
	global_load_ushort v67, v[32:33], off offset:2048
	global_load_ushort v85, v[30:31], off offset:3072
	global_load_ushort v65, v[34:35], off
	v_or_b32_e32 v30, s4, v164
	v_add_u32_e32 v30, s1, v30
	v_ashrrev_i32_e32 v31, 31, v30
	v_readlane_b32 s4, v252, 16
	v_lshlrev_b64 v[32:33], 2, v[30:31]
	v_readlane_b32 s14, v252, 26
	v_readlane_b32 s15, v252, 27
	s_waitcnt vmcnt(4)
; template <int MODE>
; __device__ __forceinline__ void lru_unit(const Args& a, int l, int b, int ch, LAS unsigned char* lds) {
;     ...
;     const float* cw = a.in[7] + (size_t)l * 4 * LW;
;     const float cw0 = cw[c], cw1 = cw[LW + c], cw2 = cw[2 * LW + c], cw3 = cw[3 * LW + c], cb = a.in[8][l * LW + c];
;     float prm[2][2][3];
; #pragma unroll
;     for (int d = 0; d < 2; ++d)
; #pragma unroll
;         for (int nt = 0; nt < 2; ++nt) { const int cc = (l * 2 + d) * LW + w * 64 + nt * 32 + r32;
;             prm[d][nt][0] = a.in[10][cc]; prm[d][nt][1] = a.in[12][cc]; prm[d][nt][2] = a.in[13][cc]; }
;     const bf16* xp = proj + (size_t)b * SEQ * DIN + c;
;     float xin[35], gl[32];
;     unsigned short xraw[35], graw[32];
; #pragma unroll
;     for (int i = 0; i < 35; ++i) { const int t = t0 - 2 + i, tc = t < 0 ? 0 : (t >= SEQ ? SEQ - 1 : t); xraw[i] = xp[(size_t)tc * DIN]; }
;     ...
;         for (int nt = 0; nt < 2; ++nt) { prm[d][nt][0] *= -1.4426950408889634f; prm[d][nt][1] *= -1.4426950408889634f;
;             prm[d][nt][2] = -8.f * 1.4426950408889634f * log1pf(__expf(-prm[d][nt][2])); }
	v_lshlrev_b32_e32 v0, 16, v0
	s_mov_b32 s1, 0xd000
	v_lshl_add_u64 v[68:69], s[14:15], 0, v[32:33]
	global_load_dword v30, v[68:69], off
	global_load_ushort v87, v[4:5], off offset:3584
	v_cndmask_b32_e32 v31, 0, v0, vcc
	v_add_co_u32_e32 v34, vcc, s1, v4
	s_mov_b32 s1, 0xe000
	s_nop 0
	v_addc_co_u32_e32 v35, vcc, 0, v5, vcc
	v_add_co_u32_e32 v36, vcc, s1, v4
	s_mov_b32 s1, 0xf000
	s_nop 0
	v_addc_co_u32_e32 v37, vcc, 0, v5, vcc
	v_add_co_u32_e32 v38, vcc, s1, v4
	s_mov_b32 s1, 0x11000
	s_nop 0
	v_addc_co_u32_e32 v39, vcc, 0, v5, vcc
	v_add_co_u32_e32 v40, vcc, s70, v4
	global_load_dword v84, v[68:69], off offset:128
	global_load_dword v88, v[68:69], off offset:2048
	global_load_dword v86, v[68:69], off offset:2176
	v_addc_co_u32_e32 v41, vcc, 0, v5, vcc
	v_add_co_u32_e32 v42, vcc, s1, v4
	s_mov_b32 s1, 0x12000
	s_nop 0
	v_addc_co_u32_e32 v43, vcc, 0, v5, vcc
	v_add_co_u32_e32 v44, vcc, s1, v4
	s_mov_b32 s1, 0x13000
	s_nop 0
	v_addc_co_u32_e32 v45, vcc, 0, v5, vcc
	v_add_co_u32_e32 v46, vcc, s1, v4
	s_mov_b32 s1, 0x14000
	s_nop 0
	v_addc_co_u32_e32 v47, vcc, 0, v5, vcc
	v_add_co_u32_e32 v48, vcc, s1, v4
	s_mov_b32 s1, 0x15000
	s_nop 0
	v_addc_co_u32_e32 v49, vcc, 0, v5, vcc
	v_add_co_u32_e32 v50, vcc, s1, v4
	s_mov_b32 s1, 0x17000
	s_nop 0
	v_addc_co_u32_e32 v51, vcc, 0, v5, vcc
	v_add_co_u32_e32 v52, vcc, s71, v4
	v_readlane_b32 s6, v252, 18
	s_nop 0
	v_addc_co_u32_e32 v53, vcc, 0, v5, vcc
	v_add_co_u32_e32 v54, vcc, s1, v4
	s_mov_b32 s1, 0x18000
	s_nop 0
	v_addc_co_u32_e32 v55, vcc, 0, v5, vcc
	v_add_co_u32_e32 v56, vcc, s1, v4
	s_mov_b32 s1, 0x19000
	s_nop 0
	v_addc_co_u32_e32 v57, vcc, 0, v5, vcc
	v_add_co_u32_e32 v58, vcc, s1, v4
	s_mov_b32 s1, 0x1b000
	s_nop 0
	v_addc_co_u32_e32 v59, vcc, 0, v5, vcc
	v_add_co_u32_e32 v60, vcc, s1, v4
	s_mov_b32 s1, 0x1a000
	s_nop 0
	v_addc_co_u32_e32 v61, vcc, 0, v5, vcc
	v_add_co_u32_e32 v62, vcc, s1, v4
	s_ashr_i32 s1, s0, 6
	s_mul_i32 s0, s1, 0x3200
	s_add_i32 s0, s0, 0
	v_addc_co_u32_e32 v63, vcc, 0, v5, vcc
	s_waitcnt vmcnt(4)
	v_mul_f32_e32 v30, 0xbfb8aa3b, v30
	v_exp_f32_e32 v30, v30
	s_cmpk_lt_u32 s28, 0x1000
	s_cselect_b64 vcc, -1, 0
	s_cmpk_lt_u32 s29, 0x1000
	v_lshlrev_b32_e32 v0, 16, v65
	v_lshlrev_b32_e32 v64, 16, v64
	s_cselect_b64 s[38:39], -1, 0
	v_cndmask_b32_e64 v65, 0, v64, s[38:39]
	v_cndmask_b32_e32 v64, 0, v0, vcc
	s_mov_b32 s6, 0x3f2aaaab
	v_readlane_b32 s7, v252, 19
	s_mov_b32 s7, 0x3f317218
	v_readlane_b32 s10, v252, 22
	s_mov_b32 s10, 0x7f800000
	v_readlane_b32 s11, v252, 23
	s_waitcnt vmcnt(2)
	v_mul_f32_e32 v68, 0xbfb8aa3b, v84
	v_exp_f32_e32 v84, v68
	s_mov_b32 s11, 0x33800000
	s_lshl_b32 s28, s1, 1
	s_ashr_i32 s29, s28, 31
	s_lshl_b64 s[28:29], s[28:29], 13
	v_readlane_b32 s1, v254, 40
	s_add_u32 s28, s1, s28
	v_add_f32_e32 v216, 1.0, v30
	v_add_f32_e32 v217, -1.0, v216
	v_log_f32_e32 v218, v216
	v_rcp_f32_e32 v219, v217
	v_cmp_eq_f32_e32 vcc, 0, v217
	v_mul_f32_e32 v218, v218, v30
	v_mul_f32_e32 v218, 0x3f317218, v218
	v_mul_f32_e32 v218, v218, v219
	v_cndmask_b32_e32 v126, v218, v30, vcc
	v_readlane_b32 s1, v254, 41
	v_bfe_u32 v165, v66, 5, 1
	s_addc_u32 s29, s1, s29
	s_waitcnt vmcnt(1)
	v_mul_f32_e32 v30, 0xbfb8aa3b, v88
	v_exp_f32_e32 v163, v30
	v_readlane_b32 s14, v254, 43
	v_readlane_b32 s5, v252, 17
	v_readlane_b32 s8, v252, 20
	v_readlane_b32 s9, v252, 21
	v_readlane_b32 s12, v252, 24
	v_readlane_b32 s13, v252, 25
	v_add_f32_e32 v216, 1.0, v84
	v_add_f32_e32 v217, -1.0, v216
	v_log_f32_e32 v218, v216
	v_rcp_f32_e32 v219, v217
	v_cmp_eq_f32_e32 vcc, 0, v217
	v_mul_f32_e32 v218, v218, v84
	v_mul_f32_e32 v218, 0x3f317218, v218
	v_mul_f32_e32 v218, v218, v219
	v_cndmask_b32_e32 v124, v218, v84, vcc
	global_load_ushort v69, v[28:29], off offset:2560
	s_nop 0
	global_load_ushort v4, v[4:5], off
	s_nop 0
	global_load_dword v28, v[24:25], off
	global_load_dword v29, v[24:25], off offset:2048
	s_nop 0
	global_load_dword v24, v[26:27], off
	global_load_dword v25, v[26:27], off offset:2048
	global_load_ushort v22, v[22:23], off offset:1536
	s_nop 0
	global_load_ushort v20, v[20:21], off offset:512
	s_nop 0
	global_load_ushort v21, v[18:19], off
	s_nop 0
	global_load_ushort v18, v[18:19], off offset:3584
	s_nop 0
	global_load_ushort v19, v[12:13], off offset:3072
	global_load_ushort v23, v[14:15], off offset:2560
	s_nop 0
	global_load_ushort v16, v[16:17], off offset:2048
	s_nop 0
	global_load_ushort v17, v[10:11], off offset:1024
	v_lshlrev_b32_e32 v0, 4, v165
	v_lshl_add_u64 v[10:11], s[28:29], 0, v[0:1]
	v_lshlrev_b32_e32 v0, 7, v164
	v_lshl_add_u64 v[90:91], v[10:11], 0, v[0:1]
	v_add_u32_e32 v10, s14, v82
	v_ashrrev_i32_e32 v11, 31, v10
	v_lshl_add_u64 v[10:11], v[10:11], 2, s[4:5]
	global_load_dword v73, v[10:11], off
	v_lshl_add_u64 v[10:11], s[8:9], 0, v[32:33]
	v_lshl_add_u64 v[12:13], s[12:13], 0, v[32:33]
	global_load_dword v128, v[10:11], off
	global_load_dword v125, v[10:11], off offset:128
	global_load_dword v161, v[10:11], off offset:2048
	global_load_dword v159, v[10:11], off offset:2176
	global_load_dword v129, v[12:13], off
	global_load_dword v127, v[12:13], off offset:128
	global_load_dword v162, v[12:13], off offset:2048
	global_load_dword v160, v[12:13], off offset:2176
	global_load_ushort v0, v[6:7], off offset:1536
	global_load_ushort v30, v[8:9], off offset:1024
	global_load_ushort v33, v[34:35], off offset:512
	s_nop 0
	global_load_ushort v34, v[36:37], off
	global_load_ushort v35, v[36:37], off offset:3584
	s_nop 0
	global_load_ushort v36, v[38:39], off offset:3072
	global_load_ushort v37, v[40:41], off offset:2560
	s_nop 0
	global_load_ushort v38, v[42:43], off offset:2048
	global_load_ushort v39, v[44:45], off offset:1536
	global_load_ushort v40, v[46:47], off offset:1024
	global_load_ushort v41, v[48:49], off offset:512
	s_nop 0
	global_load_ushort v42, v[50:51], off
	global_load_ushort v43, v[50:51], off offset:3584
	global_load_ushort v44, v[52:53], off offset:3072
	global_load_ushort v45, v[54:55], off offset:2560
	global_load_ushort v46, v[56:57], off offset:2048
	global_load_ushort v47, v[58:59], off offset:1536
	global_load_ushort v48, v[60:61], off offset:512
	global_load_ushort v49, v[62:63], off offset:1024
	v_lshlrev_b32_e32 v9, 16, v87
	v_lshlrev_b32_e32 v12, 16, v85
	v_and_b32_e32 v84, 63, v66
	v_lshl_add_u32 v32, v84, 1, s0
	v_add_co_u32_e32 v108, vcc, s60, v90
	v_lshl_add_u64 v[122:123], s[44:45], 0, v[2:3]
	s_nop 0
	v_addc_co_u32_e32 v109, vcc, 0, v91, vcc
	s_mov_b32 s1, 0x11f00000
	v_lshlrev_b64 v[82:83], 3, v[82:83]
	v_readlane_b32 s16, v252, 28
	v_readlane_b32 s17, v252, 29
	v_readlane_b32 s18, v252, 30
	v_readlane_b32 s19, v252, 31
	v_readlane_b32 s15, v254, 44
	s_mov_b64 s[8:9], s[26:27]
	s_waitcnt vmcnt(41)
; template <int MODE>
; __device__ __forceinline__ void lru_unit(const Args& a, int l, int b, int ch, LAS unsigned char* lds) {
;     ...
;     for (int i = 0; i < 35; ++i) { const int t = t0 - 2 + i; xin[i] = (t >= 0 && t < SEQ) ? bf2f(xraw[i]) : 0.f; }
;     if (MODE == 1) {
; #pragma unroll
;         for (int t = 0; t < 32; ++t) gl[t] = gelu_tanh(bf2f(graw[t]));
;     }
;     float xcr[32], hf[32];
; #pragma unroll
;     for (int t = 0; t < 32; ++t) { const float xc = cw0 * xin[t] + cw1 * xin[t + 1] + cw2 * xin[t + 2] + cw3 * xin[t + 3] + cb; xcr[t] = xc; hf[t] = 0.f;
	v_lshlrev_b32_e32 v13, 16, v69
	s_waitcnt vmcnt(40)
	v_lshlrev_b32_e32 v8, 16, v4
	s_waitcnt vmcnt(38)
	v_pk_mul_f32 v[6:7], v[28:29], v[64:65]
	s_nop 0
	v_add_f32_e32 v4, v6, v7
	s_waitcnt vmcnt(36)
	v_pk_mul_f32 v[10:11], v[24:25], v[8:9]
	v_pk_mov_b32 v[6:7], v[64:65], v[8:9] op_sel:[1,0]
	v_add_f32_e32 v4, v10, v4
	v_add_f32_e32 v4, v11, v4
	v_pk_mul_f32 v[6:7], v[28:29], v[6:7]
	v_pk_mul_f32 v[10:11], v[28:29], v[8:9]
	v_pk_mov_b32 v[8:9], v[8:9], v[12:13] op_sel:[1,0]
	v_add_f32_e32 v6, v6, v7
	v_pk_mul_f32 v[14:15], v[24:25], v[8:9]
	v_add_f32_e32 v10, v10, v11
	v_add_f32_e32 v6, v6, v14
	v_add_f32_e32 v50, v6, v15
	v_pk_mul_f32 v[6:7], v[24:25], v[12:13]
	s_waitcnt vmcnt(35)
	v_lshlrev_b32_e32 v11, 16, v22
	v_add_f32_e32 v6, v10, v6
	v_lshlrev_b32_e32 v10, 16, v67
	v_add_f32_e32 v51, v6, v7
	v_pk_mul_f32 v[6:7], v[28:29], v[8:9]
	v_pk_mul_f32 v[8:9], v[28:29], v[12:13]
	v_pk_mov_b32 v[12:13], v[12:13], v[10:11] op_sel:[1,0]
	v_add_f32_e32 v6, v6, v7
	v_pk_mul_f32 v[14:15], v[24:25], v[12:13]
	v_add_f32_e32 v8, v8, v9
	v_add_f32_e32 v6, v6, v14
	v_add_f32_e32 v22, v6, v15
	v_pk_mul_f32 v[6:7], v[24:25], v[10:11]
	s_waitcnt vmcnt(27)
	v_add_f32_e32 v85, v73, v4
	v_add_f32_e32 v6, v8, v6
	v_add_f32_e32 v52, v6, v7
	v_pk_mul_f32 v[6:7], v[28:29], v[12:13]
	v_lshlrev_b32_e32 v13, 16, v20
	v_lshlrev_b32_e32 v12, 16, v17
	v_pk_mul_f32 v[8:9], v[28:29], v[10:11]
	v_pk_mov_b32 v[10:11], v[10:11], v[12:13] op_sel:[1,0]
	v_add_f32_e32 v6, v6, v7
	v_pk_mul_f32 v[14:15], v[24:25], v[10:11]
	v_add_f32_e32 v8, v8, v9
	v_add_f32_e32 v6, v6, v14
	v_add_f32_e32 v17, v6, v15
	v_pk_mul_f32 v[6:7], v[24:25], v[12:13]
	v_add_f32_e32 v130, v73, v51
	v_add_f32_e32 v6, v8, v6
	v_add_f32_e32 v20, v6, v7
	v_pk_mul_f32 v[6:7], v[28:29], v[10:11]
	v_lshlrev_b32_e32 v11, 16, v18
	v_lshlrev_b32_e32 v10, 16, v21
	v_pk_mul_f32 v[8:9], v[28:29], v[12:13]
	v_pk_mov_b32 v[12:13], v[12:13], v[10:11] op_sel:[1,0]
	v_add_f32_e32 v6, v6, v7
	v_pk_mul_f32 v[14:15], v[24:25], v[12:13]
	v_add_f32_e32 v8, v8, v9
	v_add_f32_e32 v6, v6, v14
	v_add_f32_e32 v18, v6, v15
	v_pk_mul_f32 v[6:7], v[24:25], v[10:11]
	v_add_f32_e32 v131, v73, v22
	v_add_f32_e32 v6, v8, v6
	v_add_f32_e32 v21, v6, v7
	v_pk_mul_f32 v[6:7], v[28:29], v[12:13]
	v_lshlrev_b32_e32 v13, 16, v23
	v_lshlrev_b32_e32 v12, 16, v19
	v_pk_mul_f32 v[8:9], v[28:29], v[10:11]
	v_pk_mov_b32 v[10:11], v[10:11], v[12:13] op_sel:[1,0]
	v_add_f32_e32 v6, v6, v7
	v_pk_mul_f32 v[14:15], v[24:25], v[10:11]
	v_add_f32_e32 v8, v8, v9
	v_add_f32_e32 v6, v6, v14
	v_add_f32_e32 v19, v6, v15
	v_pk_mul_f32 v[6:7], v[24:25], v[12:13]
	v_add_f32_e32 v132, v73, v52
	v_add_f32_e32 v6, v8, v6
	v_add_f32_e32 v23, v6, v7
	v_pk_mul_f32 v[6:7], v[28:29], v[10:11]
	s_waitcnt vmcnt(18)
	v_lshlrev_b32_e32 v11, 16, v0
	v_lshlrev_b32_e32 v10, 16, v16
	v_pk_mul_f32 v[8:9], v[28:29], v[12:13]
	v_pk_mov_b32 v[12:13], v[12:13], v[10:11] op_sel:[1,0]
	v_add_f32_e32 v0, v6, v7
	v_pk_mul_f32 v[14:15], v[24:25], v[12:13]
	v_pk_mul_f32 v[6:7], v[24:25], v[10:11]
	v_add_f32_e32 v0, v0, v14
	v_add_f32_e32 v16, v0, v15
	v_add_f32_e32 v0, v8, v9
	v_add_f32_e32 v0, v0, v6
	v_add_f32_e32 v53, v0, v7
	v_pk_mul_f32 v[6:7], v[28:29], v[12:13]
	s_waitcnt vmcnt(16)
	v_lshlrev_b32_e32 v13, 16, v33
	v_lshlrev_b32_e32 v12, 16, v30
	v_pk_mul_f32 v[8:9], v[28:29], v[10:11]
	v_pk_mov_b32 v[10:11], v[10:11], v[12:13] op_sel:[1,0]
	v_add_f32_e32 v0, v6, v7
	v_pk_mul_f32 v[14:15], v[24:25], v[10:11]
	v_pk_mul_f32 v[6:7], v[24:25], v[12:13]
	v_add_f32_e32 v0, v0, v14
	v_add_f32_e32 v33, v0, v15
	v_add_f32_e32 v0, v8, v9
	v_add_f32_e32 v0, v0, v6
	v_add_f32_e32 v54, v0, v7
	v_pk_mul_f32 v[6:7], v[28:29], v[10:11]
	s_waitcnt vmcnt(14)
	v_lshlrev_b32_e32 v11, 16, v35
	v_lshlrev_b32_e32 v10, 16, v34
	v_pk_mul_f32 v[8:9], v[28:29], v[12:13]
	v_pk_mov_b32 v[12:13], v[12:13], v[10:11] op_sel:[1,0]
	v_add_f32_e32 v0, v6, v7
	v_pk_mul_f32 v[14:15], v[24:25], v[12:13]
	v_pk_mul_f32 v[6:7], v[24:25], v[10:11]
	v_add_f32_e32 v0, v0, v14
	v_add_f32_e32 v34, v0, v15
	v_add_f32_e32 v0, v8, v9
	v_add_f32_e32 v0, v0, v6
	v_add_f32_e32 v35, v0, v7
	v_pk_mul_f32 v[6:7], v[28:29], v[12:13]
	s_waitcnt vmcnt(12)
	v_lshlrev_b32_e32 v13, 16, v37
	v_lshlrev_b32_e32 v12, 16, v36
	v_pk_mul_f32 v[8:9], v[28:29], v[10:11]
	v_pk_mov_b32 v[10:11], v[10:11], v[12:13] op_sel:[1,0]
	v_add_f32_e32 v0, v6, v7
	v_pk_mul_f32 v[14:15], v[24:25], v[10:11]
	v_pk_mul_f32 v[6:7], v[24:25], v[12:13]
	v_add_f32_e32 v0, v0, v14
	v_add_f32_e32 v36, v0, v15
	v_add_f32_e32 v0, v8, v9
	v_add_f32_e32 v0, v0, v6
	v_add_f32_e32 v37, v0, v7
	v_pk_mul_f32 v[6:7], v[28:29], v[10:11]
	s_waitcnt vmcnt(10)
	v_lshlrev_b32_e32 v11, 16, v39
	v_lshlrev_b32_e32 v10, 16, v38
	v_pk_mul_f32 v[8:9], v[28:29], v[12:13]
	v_pk_mov_b32 v[12:13], v[12:13], v[10:11] op_sel:[1,0]
	v_add_f32_e32 v0, v6, v7
	v_pk_mul_f32 v[14:15], v[24:25], v[12:13]
	v_pk_mul_f32 v[6:7], v[24:25], v[10:11]
	v_add_f32_e32 v0, v0, v14
	v_add_f32_e32 v38, v0, v15
	v_add_f32_e32 v0, v8, v9
	v_add_f32_e32 v0, v0, v6
	v_add_f32_e32 v39, v0, v7
	v_pk_mul_f32 v[6:7], v[28:29], v[12:13]
	s_waitcnt vmcnt(8)
	v_lshlrev_b32_e32 v13, 16, v41
	v_lshlrev_b32_e32 v12, 16, v40
	v_pk_mul_f32 v[8:9], v[28:29], v[10:11]
	v_pk_mov_b32 v[10:11], v[10:11], v[12:13] op_sel:[1,0]
	v_add_f32_e32 v0, v6, v7
	v_pk_mul_f32 v[14:15], v[24:25], v[10:11]
	v_pk_mul_f32 v[6:7], v[24:25], v[12:13]
	v_add_f32_e32 v0, v0, v14
	v_add_f32_e32 v40, v0, v15
	v_add_f32_e32 v0, v8, v9
	v_add_f32_e32 v0, v0, v6
	v_add_f32_e32 v41, v0, v7
	v_pk_mul_f32 v[6:7], v[28:29], v[10:11]
	s_waitcnt vmcnt(6)
; #define LAS __attribute__((address_space(3)))
; __device__ __forceinline__ unsigned f2bf(float f) { unsigned u = __builtin_bit_cast(unsigned, f); return (u + 0x7fffu + ((u >> 16) & 1u)) >> 16; }
; #define LDS_WAVE_SYNC() asm volatile("s_waitcnt lgkmcnt(0)" ::: "memory")
; template <int MODE>
; __device__ __forceinline__ void lru_unit(const Args& a, int l, int b, int ch, LAS unsigned char* lds) {
;     ...
;     for (int t = 0; t < 32; ++t) { const float xc = cw0 * xin[t] + cw1 * xin[t + 1] + cw2 * xin[t + 2] + cw3 * xin[t + 3] + cb; xcr[t] = xc; hf[t] = 0.f;
;         *(LAS bf16*)(xcb + t * 144 + lane * 2) = (bf16)f2bf(xc); }
; #pragma unroll
;     for (int d = 0; d < 2; ++d)
; #pragma unroll
;         for (int nt = 0; nt < 2; ++nt) { prm[d][nt][0] *= -1.4426950408889634f; prm[d][nt][1] *= -1.4426950408889634f;
;             prm[d][nt][2] = -8.f * 1.4426950408889634f * log1pf(__expf(-prm[d][nt][2])); }
;     LDS_WAVE_SYNC();
	v_lshlrev_b32_e32 v11, 16, v43
	v_lshlrev_b32_e32 v10, 16, v42
	v_pk_mul_f32 v[8:9], v[28:29], v[12:13]
	v_pk_mov_b32 v[12:13], v[12:13], v[10:11] op_sel:[1,0]
	v_add_f32_e32 v0, v6, v7
	v_pk_mul_f32 v[14:15], v[24:25], v[12:13]
	v_pk_mul_f32 v[6:7], v[24:25], v[10:11]
	v_add_f32_e32 v0, v0, v14
	v_add_f32_e32 v42, v0, v15
	v_add_f32_e32 v0, v8, v9
	v_add_f32_e32 v0, v0, v6
	v_add_f32_e32 v43, v0, v7
	v_pk_mul_f32 v[6:7], v[28:29], v[12:13]
	s_waitcnt vmcnt(4)
	v_lshlrev_b32_e32 v13, 16, v45
	v_lshlrev_b32_e32 v12, 16, v44
	v_pk_mul_f32 v[8:9], v[28:29], v[10:11]
	v_pk_mov_b32 v[10:11], v[10:11], v[12:13] op_sel:[1,0]
	v_add_f32_e32 v0, v6, v7
	v_pk_mul_f32 v[14:15], v[24:25], v[10:11]
	v_pk_mul_f32 v[6:7], v[24:25], v[12:13]
	v_add_f32_e32 v0, v0, v14
	v_add_f32_e32 v44, v0, v15
	v_add_f32_e32 v0, v8, v9
	v_add_f32_e32 v0, v0, v6
	v_add_f32_e32 v45, v0, v7
	v_pk_mul_f32 v[6:7], v[28:29], v[10:11]
	s_waitcnt vmcnt(2)
	v_lshlrev_b32_e32 v11, 16, v47
	v_lshlrev_b32_e32 v10, 16, v46
	v_pk_mul_f32 v[8:9], v[28:29], v[12:13]
	v_pk_mov_b32 v[12:13], v[12:13], v[10:11] op_sel:[1,0]
	v_add_f32_e32 v0, v6, v7
	v_pk_mul_f32 v[14:15], v[24:25], v[12:13]
	v_pk_mul_f32 v[6:7], v[24:25], v[10:11]
	v_add_f32_e32 v0, v0, v14
	v_add_f32_e32 v46, v0, v15
	v_add_f32_e32 v0, v8, v9
	v_add_f32_e32 v0, v0, v6
	v_add_f32_e32 v47, v0, v7
	v_pk_mul_f32 v[6:7], v[28:29], v[12:13]
	s_waitcnt vmcnt(0)
	v_lshlrev_b32_e32 v12, 16, v49
	v_lshlrev_b32_e32 v13, 16, v48
	v_pk_mul_f32 v[8:9], v[28:29], v[10:11]
	v_pk_mov_b32 v[10:11], v[10:11], v[12:13] op_sel:[1,0]
	v_add_f32_e32 v0, v6, v7
	v_pk_mul_f32 v[14:15], v[24:25], v[10:11]
	v_pk_mul_f32 v[6:7], v[24:25], v[12:13]
	v_add_f32_e32 v0, v0, v14
	v_add_f32_e32 v14, v0, v15
	v_add_f32_e32 v0, v8, v9
	v_add_f32_e32 v0, v0, v6
	v_add_f32_e32 v12, v0, v7
	v_pk_mul_f32 v[6:7], v[28:29], v[10:11]
	v_mov_b32_e32 v30, v13
	v_pk_mul_f32 v[8:9], v[24:25], v[30:31]
	v_add_f32_e32 v0, v6, v7
	v_add_f32_e32 v0, v0, v8
	v_add_f32_e32 v0, v0, v9
	v_add_f32_e32 v87, v73, v0
	v_bfe_u32 v0, v87, 16, 1
	v_add3_u32 v0, v87, v0, s91
	ds_write_b16_d16_hi v32, v0 offset:4464
	v_bfe_u32 v0, v85, 16, 1
	v_add3_u32 v0, v85, v0, s91
	ds_write_b16_d16_hi v32, v0
	v_add_f32_e32 v0, v73, v50
	v_bfe_u32 v4, v0, 16, 1
	v_add3_u32 v4, v0, v4, s91
	ds_write_b16_d16_hi v32, v4 offset:144
	v_bfe_u32 v4, v130, 16, 1
	v_add3_u32 v4, v130, v4, s91
	ds_write_b16_d16_hi v32, v4 offset:288
	v_bfe_u32 v4, v131, 16, 1
	v_add3_u32 v4, v131, v4, s91
	ds_write_b16_d16_hi v32, v4 offset:432
	v_bfe_u32 v4, v132, 16, 1
	v_add3_u32 v4, v132, v4, s91
	v_add_f32_e32 v133, v73, v17
	ds_write_b16_d16_hi v32, v4 offset:576
	v_bfe_u32 v4, v133, 16, 1
	v_add3_u32 v4, v133, v4, s91
	v_add_f32_e32 v134, v73, v20
	ds_write_b16_d16_hi v32, v4 offset:720
	v_bfe_u32 v4, v134, 16, 1
	v_add3_u32 v4, v134, v4, s91
	v_add_f32_e32 v135, v73, v18
	ds_write_b16_d16_hi v32, v4 offset:864
	v_bfe_u32 v4, v135, 16, 1
	v_add3_u32 v4, v135, v4, s91
	v_add_f32_e32 v136, v73, v21
	ds_write_b16_d16_hi v32, v4 offset:1008
	v_bfe_u32 v4, v136, 16, 1
	v_add3_u32 v4, v136, v4, s91
	v_add_f32_e32 v137, v73, v19
	ds_write_b16_d16_hi v32, v4 offset:1152
	v_bfe_u32 v4, v137, 16, 1
	v_add3_u32 v4, v137, v4, s91
	v_add_f32_e32 v138, v73, v23
	ds_write_b16_d16_hi v32, v4 offset:1296
	v_bfe_u32 v4, v138, 16, 1
	v_add3_u32 v4, v138, v4, s91
	v_add_f32_e32 v139, v73, v16
	ds_write_b16_d16_hi v32, v4 offset:1440
	v_bfe_u32 v4, v139, 16, 1
	v_add3_u32 v4, v139, v4, s91
	v_add_f32_e32 v140, v73, v53
	ds_write_b16_d16_hi v32, v4 offset:1584
	v_bfe_u32 v4, v140, 16, 1
	v_add3_u32 v4, v140, v4, s91
	v_add_f32_e32 v141, v73, v33
	ds_write_b16_d16_hi v32, v4 offset:1728
	v_bfe_u32 v4, v141, 16, 1
	v_add3_u32 v4, v141, v4, s91
	v_add_f32_e32 v142, v73, v54
	ds_write_b16_d16_hi v32, v4 offset:1872
	v_bfe_u32 v4, v142, 16, 1
	v_add3_u32 v4, v142, v4, s91
	v_add_f32_e32 v143, v73, v34
	ds_write_b16_d16_hi v32, v4 offset:2016
	v_bfe_u32 v4, v143, 16, 1
	v_add3_u32 v4, v143, v4, s91
	v_add_f32_e32 v144, v73, v35
	ds_write_b16_d16_hi v32, v4 offset:2160
	v_bfe_u32 v4, v144, 16, 1
	v_add3_u32 v4, v144, v4, s91
	v_add_f32_e32 v145, v73, v36
	ds_write_b16_d16_hi v32, v4 offset:2304
	v_bfe_u32 v4, v145, 16, 1
	v_add3_u32 v4, v145, v4, s91
	v_add_f32_e32 v146, v73, v37
	ds_write_b16_d16_hi v32, v4 offset:2448
	v_bfe_u32 v4, v146, 16, 1
	v_add3_u32 v4, v146, v4, s91
	v_add_f32_e32 v147, v73, v38
	ds_write_b16_d16_hi v32, v4 offset:2592
	v_bfe_u32 v4, v147, 16, 1
	v_add3_u32 v4, v147, v4, s91
	v_add_f32_e32 v148, v73, v39
	ds_write_b16_d16_hi v32, v4 offset:2736
	v_bfe_u32 v4, v148, 16, 1
	v_add3_u32 v4, v148, v4, s91
	v_add_f32_e32 v149, v73, v40
	ds_write_b16_d16_hi v32, v4 offset:2880
	v_bfe_u32 v4, v149, 16, 1
	v_add3_u32 v4, v149, v4, s91
	v_add_f32_e32 v150, v73, v41
	ds_write_b16_d16_hi v32, v4 offset:3024
	v_bfe_u32 v4, v150, 16, 1
	v_add3_u32 v4, v150, v4, s91
	v_add_f32_e32 v151, v73, v42
	ds_write_b16_d16_hi v32, v4 offset:3168
	v_bfe_u32 v4, v151, 16, 1
	v_add3_u32 v4, v151, v4, s91
	v_add_f32_e32 v152, v73, v43
	ds_write_b16_d16_hi v32, v4 offset:3312
	v_bfe_u32 v4, v152, 16, 1
	v_add3_u32 v4, v152, v4, s91
	v_add_f32_e32 v153, v73, v44
	ds_write_b16_d16_hi v32, v4 offset:3456
	v_bfe_u32 v4, v153, 16, 1
	v_add3_u32 v4, v153, v4, s91
	v_add_f32_e32 v154, v73, v45
	ds_write_b16_d16_hi v32, v4 offset:3600
	v_bfe_u32 v4, v154, 16, 1
	v_add3_u32 v4, v154, v4, s91
	v_add_f32_e32 v155, v73, v46
	ds_write_b16_d16_hi v32, v4 offset:3744
	v_bfe_u32 v4, v155, 16, 1
	v_add3_u32 v4, v155, v4, s91
	v_add_f32_e32 v156, v73, v47
	ds_write_b16_d16_hi v32, v4 offset:3888
	v_bfe_u32 v4, v156, 16, 1
	v_add3_u32 v4, v156, v4, s91
	v_add_f32_e32 v157, v73, v14
	ds_write_b16_d16_hi v32, v4 offset:4032
	v_bfe_u32 v4, v157, 16, 1
	v_add3_u32 v4, v157, v4, s91
	v_add_f32_e32 v158, v73, v12
	ds_write_b16_d16_hi v32, v4 offset:4176
	v_bfe_u32 v4, v158, 16, 1
	v_add3_u32 v4, v158, v4, s91
	ds_write_b16_d16_hi v32, v4 offset:4320
	s_waitcnt lgkmcnt(0)
; #define MFMA32(a, b, c) __builtin_amdgcn_mfma_f32_32x32x16_bf16((a), (b), (c), 0, 0, 0)
; template <int DIR, int MODE> ...
;     ...
;         const bf16* wr_ = wl + (size_t)((DIR * 8 + w) * 2) * 4096 + (nt * 32 + r32) * 64 + 8 * h;
; #pragma unroll
;         for (int ks = 0; ks < 4; ++ks) {
;             const bf16x8 bR = *(const bf16x8*)(wr_ + 16 * ks), bI = *(const bf16x8*)(wr_ + 4096 + 16 * ks);
;             accR[nt] = MFMA32(af[ks], bR, accR[nt]); accI[nt] = MFMA32(af[ks], bI, accI[nt]); }
;     }
; #pragma unroll
;     for (int nt = 0; nt < 2; ++nt) {
;         const float nba = prm[DIR][nt][0], nbx = prm[DIR][nt][1], k8l = prm[DIR][nt][2];
; #pragma unroll
;         for (int i = 0; i < 16; ++i) {
;             const float d1 = 1.f + __builtin_amdgcn_exp2f(__builtin_fmaf(accR[nt][i], -1.4426950408889634f, nba));
;             const float d2 = 1.f + __builtin_amdgcn_exp2f(__builtin_fmaf(accI[nt][i], -1.4426950408889634f, nbx));
;             const float inv = __builtin_amdgcn_rcpf(d1 * d2), rr = inv * d2, ii = inv * d1;
;             const float av = __builtin_amdgcn_exp2f(k8l * rr);
;             accR[nt][i] = av; accI[nt][i] = __builtin_amdgcn_sqrtf(fmaxf(__builtin_fmaf(-av, av, 1.f), 0.f)) * ii; }
	global_load_dwordx4 v[6:9], v[90:91], off
	global_load_dwordx4 v[10:13], v[108:109], off offset:-4096
	v_add_co_u32_e32 v34, vcc, s59, v90
	s_nop 1
	v_addc_co_u32_e32 v35, vcc, 0, v91, vcc
	global_load_dwordx4 v[14:17], v[90:91], off offset:32
	global_load_dwordx4 v[18:21], v[34:35], off offset:32
	global_load_dwordx4 v[22:25], v[90:91], off offset:64
	global_load_dwordx4 v[26:29], v[34:35], off offset:64
	global_load_dwordx4 v[30:33], v[90:91], off offset:96
	global_load_dwordx4 v[104:107], v[34:35], off offset:96
	v_add_co_u32_e32 v74, vcc, s61, v90
	s_nop 0
	s_nop 0
	v_addc_co_u32_e32 v75, vcc, 0, v91, vcc
	global_load_dwordx4 v[166:169], v[74:75], off
	global_load_dwordx4 v[174:177], v[74:75], off offset:32
	global_load_dwordx4 v[182:185], v[74:75], off offset:64
	v_lshrrev_b32_e32 v5, 1, v66
	v_mul_u32_u24_e32 v4, 0x90, v164
	v_and_b32_e32 v5, 16, v5
	v_add3_u32 v110, s0, v4, v5
	ds_read_b128 v[70:73], v110
	ds_read_b128 v[66:69], v110 offset:32
	global_load_dwordx4 v[170:173], v[74:75], off offset:96
	s_waitcnt vmcnt(11) lgkmcnt(1)
	v_mfma_f32_32x32x16_bf16 v[34:49], v[70:73], v[6:9], 0
	global_load_dwordx4 v[4:7], v[108:109], off
	global_load_dwordx4 v[178:181], v[108:109], off offset:32
	s_waitcnt vmcnt(12)
	v_mfma_f32_32x32x16_bf16 v[50:65], v[70:73], v[10:13], 0
	ds_read_b128 v[74:77], v110 offset:96
	ds_read_b128 v[78:81], v110 offset:64
	s_waitcnt vmcnt(11) lgkmcnt(2)
	v_mfma_f32_32x32x16_bf16 v[34:49], v[66:69], v[14:17], v[34:49]
	v_mul_f32_e32 v97, 0xbfb8aa3b, v128
	global_load_dwordx4 v[186:189], v[108:109], off offset:64
	global_load_dwordx4 v[200:203], v[108:109], off offset:96
	s_waitcnt vmcnt(12)
	v_mfma_f32_32x32x16_bf16 v[50:65], v[66:69], v[18:21], v[50:65]
	v_mul_f32_e32 v99, 0xbfb8aa3b, v129
	v_mul_f32_e32 v93, 0xbfb8aa3b, v127
	v_lshl_add_u64 v[88:89], s[46:47], 0, v[2:3]
	v_mul_f32_e32 v95, 0xbfb8aa3b, v125
	v_add_co_u32_e32 v120, vcc, s1, v88
	s_waitcnt vmcnt(11) lgkmcnt(0)
	v_mfma_f32_32x32x16_bf16 v[34:49], v[78:81], v[22:25], v[34:49]
	v_addc_co_u32_e32 v121, vcc, 0, v89, vcc
	s_mov_b32 s1, 0x11f01000
	v_add_co_u32_e32 v118, vcc, s1, v88
	s_mov_b32 s1, 0x11f02000
	s_nop 0
	v_addc_co_u32_e32 v119, vcc, 0, v89, vcc
	s_waitcnt vmcnt(10)
	v_mfma_f32_32x32x16_bf16 v[50:65], v[78:81], v[26:29], v[50:65]
	v_add_co_u32_e32 v116, vcc, s1, v88
	s_mov_b32 s1, 0x11f03000
	s_nop 0
	v_addc_co_u32_e32 v117, vcc, 0, v89, vcc
	v_add_co_u32_e32 v114, vcc, s1, v88
	s_waitcnt vmcnt(9)
	v_mfma_f32_32x32x16_bf16 v[34:49], v[74:77], v[30:33], v[34:49]
	v_addc_co_u32_e32 v115, vcc, 0, v89, vcc
	s_mov_b32 s1, 0x11f04000
	v_add_co_u32_e32 v112, vcc, s1, v88
	s_mov_b32 s1, 0x11f05000
	s_nop 0
	v_addc_co_u32_e32 v113, vcc, 0, v89, vcc
	s_waitcnt vmcnt(8)
	v_mfma_f32_32x32x16_bf16 v[50:65], v[74:77], v[104:107], v[50:65]
	s_nop 3
	v_fmamk_f32 v34, v34, 0xbfb8aa3b, v97
	v_fmamk_f32 v101, v35, 0xbfb8aa3b, v97
	v_exp_f32_e32 v34, v34
	v_fmamk_f32 v129, v36, 0xbfb8aa3b, v97
	v_fmamk_f32 v38, v38, 0xbfb8aa3b, v97
	v_fmamk_f32 v39, v39, 0xbfb8aa3b, v97
	v_fmamk_f32 v40, v40, 0xbfb8aa3b, v97
	s_nop 0
	v_fmamk_f32 v50, v50, 0xbfb8aa3b, v99
	v_exp_f32_e32 v35, v50
	v_fmamk_f32 v51, v51, 0xbfb8aa3b, v99
	s_waitcnt vmcnt(7)
	v_mfma_f32_32x32x16_bf16 v[18:33], v[70:73], v[166:169], 0
	v_fmamk_f32 v166, v37, 0xbfb8aa3b, v97
	v_add_f32_e64 v34, v34, 1.0
	v_add_f32_e64 v35, v35, 1.0
	v_exp_f32_e32 v37, v51
	v_mul_f32_e32 v36, v34, v35
	v_rcp_f32_e32 v193, v36
	v_exp_f32_e32 v36, v101
	v_mov_b32_e32 v127, v35
	v_fmamk_f32 v41, v41, 0xbfb8aa3b, v97
	v_fmamk_f32 v42, v42, 0xbfb8aa3b, v97
	v_fmamk_f32 v43, v43, 0xbfb8aa3b, v97
	v_fmamk_f32 v44, v44, 0xbfb8aa3b, v97
	v_fmamk_f32 v45, v45, 0xbfb8aa3b, v97
	v_fmamk_f32 v46, v46, 0xbfb8aa3b, v97
	v_fmamk_f32 v167, v47, 0xbfb8aa3b, v97
	v_fmamk_f32 v168, v48, 0xbfb8aa3b, v97
	v_fmac_f32_e32 v97, 0xbfb8aa3b, v49
	v_pk_mul_f32 v[48:49], v[126:127], v[192:193]
	v_pk_add_f32 v[36:37], v[36:37], 1.0 op_sel_hi:[1,0]
	v_mul_f32_e32 v35, v48, v49
	v_exp_f32_e32 v128, v35
	v_mul_f32_e32 v35, v36, v37
	v_rcp_f32_e32 v49, v35
	v_mul_f32_e32 v50, v34, v193
	v_fma_f32 v34, -v128, v128, 1.0
	v_fmamk_f32 v47, v52, 0xbfb8aa3b, v99
	v_mul_f32_e32 v35, v37, v49
	v_mul_f32_e32 v35, v48, v35
	v_exp_f32_e32 v126, v35
	v_max_f32_e32 v34, 0, v34
	v_sqrt_f32_e32 v37, v34
	v_exp_f32_e32 v34, v129
	v_exp_f32_e32 v35, v47
	v_fma_f32 v47, -v126, v126, 1.0
	v_max_f32_e32 v47, 0, v47
	v_sqrt_f32_e32 v47, v47
	v_pk_add_f32 v[34:35], v[34:35], 1.0 op_sel_hi:[1,0]
	v_fmamk_f32 v52, v53, 0xbfb8aa3b, v99
	v_mul_f32_e32 v51, v34, v35
	v_rcp_f32_e32 v51, v51
	v_mul_f32_e32 v36, v36, v49
	v_mul_f32_e32 v129, v50, v37
	v_mul_f32_e32 v127, v36, v47
	v_exp_f32_e32 v36, v166
	v_exp_f32_e32 v37, v52
	v_mul_f32_e32 v35, v35, v51
	v_mul_f32_e32 v35, v48, v35
	s_waitcnt vmcnt(6)
; #define MFMA32(a, b, c) __builtin_amdgcn_mfma_f32_32x32x16_bf16((a), (b), (c), 0, 0, 0)
; template <int DIR, int MODE> ...
;     ...
;             accR[nt] = MFMA32(af[ks], bR, accR[nt]); accI[nt] = MFMA32(af[ks], bI, accI[nt]); }
;     }
; #pragma unroll
;     for (int nt = 0; nt < 2; ++nt) {
;         const float nba = prm[DIR][nt][0], nbx = prm[DIR][nt][1], k8l = prm[DIR][nt][2];
; #pragma unroll
;         for (int i = 0; i < 16; ++i) {
;             const float d1 = 1.f + __builtin_amdgcn_exp2f(__builtin_fmaf(accR[nt][i], -1.4426950408889634f, nba));
;             const float d2 = 1.f + __builtin_amdgcn_exp2f(__builtin_fmaf(accI[nt][i], -1.4426950408889634f, nbx));
;             const float inv = __builtin_amdgcn_rcpf(d1 * d2), rr = inv * d2, ii = inv * d1;
;             const float av = __builtin_amdgcn_exp2f(k8l * rr);
;             accR[nt][i] = av; accI[nt][i] = __builtin_amdgcn_sqrtf(fmaxf(__builtin_fmaf(-av, av, 1.f), 0.f)) * ii; }
	v_mfma_f32_32x32x16_bf16 v[18:33], v[66:69], v[174:177], v[18:33]
	v_add_f32_e64 v36, v36, 1.0
	v_add_f32_e64 v37, v37, 1.0
	v_fmamk_f32 v176, v62, 0xbfb8aa3b, v99
	v_exp_f32_e32 v62, v35
	v_mul_f32_e32 v35, v36, v37
	v_rcp_f32_e32 v47, v35
	v_fmamk_f32 v53, v54, 0xbfb8aa3b, v99
	v_mul_f32_e32 v49, v34, v51
	v_fma_f32 v34, -v62, v62, 1.0
	v_mul_f32_e32 v35, v37, v47
	v_mul_f32_e32 v35, v48, v35
	v_exp_f32_e32 v54, v35
	v_max_f32_e32 v34, 0, v34
	v_sqrt_f32_e32 v37, v34
	v_exp_f32_e32 v34, v38
	v_exp_f32_e32 v35, v53
	v_fma_f32 v38, -v54, v54, 1.0
	v_max_f32_e32 v38, 0, v38
	v_sqrt_f32_e32 v38, v38
	v_pk_add_f32 v[34:35], v[34:35], 1.0 op_sel_hi:[1,0]
	v_fmamk_f32 v169, v55, 0xbfb8aa3b, v99
	v_mul_f32_e32 v50, v34, v35
	v_rcp_f32_e32 v51, v50
	v_mul_f32_e32 v36, v36, v47
	v_fmamk_f32 v177, v63, 0xbfb8aa3b, v99
	v_mul_f32_e32 v63, v49, v37
	v_mul_f32_e32 v55, v36, v38
	v_exp_f32_e32 v36, v39
	v_exp_f32_e32 v37, v169
	v_mul_f32_e32 v35, v35, v51
	v_mul_f32_e32 v35, v48, v35
	v_exp_f32_e32 v50, v35
	v_pk_add_f32 v[36:37], v[36:37], 1.0 op_sel_hi:[1,0]
	v_mul_f32_e32 v39, v34, v51
	v_mul_f32_e32 v35, v36, v37
	v_rcp_f32_e32 v38, v35
	v_fma_f32 v34, -v50, v50, 1.0
	v_fmamk_f32 v56, v56, 0xbfb8aa3b, v99
	v_max_f32_e32 v34, 0, v34
	v_mul_f32_e32 v35, v37, v38
	v_mul_f32_e32 v35, v48, v35
	v_exp_f32_e32 v52, v35
	v_sqrt_f32_e32 v37, v34
	v_exp_f32_e32 v34, v40
	v_exp_f32_e32 v35, v56
	v_fma_f32 v40, -v52, v52, 1.0
	v_max_f32_e32 v40, 0, v40
	v_sqrt_f32_e32 v40, v40
	v_pk_add_f32 v[34:35], v[34:35], 1.0 op_sel_hi:[1,0]
	v_fmamk_f32 v57, v57, 0xbfb8aa3b, v99
	v_mul_f32_e32 v47, v34, v35
	v_rcp_f32_e32 v47, v47
	v_mul_f32_e32 v36, v36, v38
	v_mul_f32_e32 v51, v39, v37
	v_mul_f32_e32 v53, v36, v40
	v_exp_f32_e32 v36, v41
	v_exp_f32_e32 v37, v57
	v_mul_f32_e32 v35, v35, v47
	v_mul_f32_e32 v35, v48, v35
	v_exp_f32_e32 v56, v35
	v_pk_add_f32 v[36:37], v[36:37], 1.0 op_sel_hi:[1,0]
	v_fmamk_f32 v174, v58, 0xbfb8aa3b, v99
	v_mul_f32_e32 v35, v36, v37
	v_rcp_f32_e32 v40, v35
	v_mul_f32_e32 v41, v34, v47
	v_fma_f32 v34, -v56, v56, 1.0
	v_max_f32_e32 v34, 0, v34
	v_mul_f32_e32 v35, v37, v40
	v_mul_f32_e32 v35, v48, v35
	v_exp_f32_e32 v58, v35
	v_sqrt_f32_e32 v37, v34
	v_exp_f32_e32 v34, v42
	v_exp_f32_e32 v35, v174
	v_fma_f32 v38, -v58, v58, 1.0
	v_max_f32_e32 v38, 0, v38
	v_sqrt_f32_e32 v42, v38
	v_pk_add_f32 v[38:39], v[34:35], 1.0 op_sel_hi:[1,0]
	v_fmamk_f32 v175, v59, 0xbfb8aa3b, v99
	v_mul_f32_e32 v34, v38, v39
	v_rcp_f32_e32 v35, v34
	v_mul_f32_e32 v57, v41, v37
	v_mul_f32_e32 v34, v36, v40
	v_exp_f32_e32 v36, v43
	v_exp_f32_e32 v37, v175
	v_mul_f32_e32 v59, v34, v42
	v_mul_f32_e32 v34, v39, v35
	v_mul_f32_e32 v34, v48, v34
	v_pk_add_f32 v[40:41], v[36:37], 1.0 op_sel_hi:[1,0]
	v_exp_f32_e32 v34, v34
	v_mul_f32_e32 v36, v40, v41
	v_rcp_f32_e32 v37, v36
	v_mul_f32_e32 v35, v38, v35
	v_fma_f32 v36, -v34, v34, 1.0
	v_max_f32_e32 v38, 0, v36
	v_mul_f32_e32 v36, v41, v37
	v_mul_f32_e32 v36, v48, v36
	v_exp_f32_e32 v36, v36
	v_fmamk_f32 v60, v60, 0xbfb8aa3b, v99
	v_sqrt_f32_e32 v41, v38
	v_exp_f32_e32 v38, v44
	v_exp_f32_e32 v39, v60
	v_fma_f32 v42, -v36, v36, 1.0
	v_max_f32_e32 v42, 0, v42
	v_sqrt_f32_e32 v44, v42
	v_pk_add_f32 v[42:43], v[38:39], 1.0 op_sel_hi:[1,0]
	v_fmamk_f32 v61, v61, 0xbfb8aa3b, v99
	v_mul_f32_e32 v38, v42, v43
	v_rcp_f32_e32 v39, v38
	v_mul_f32_e32 v35, v35, v41
	v_mul_f32_e32 v37, v40, v37
	v_exp_f32_e32 v40, v45
	v_exp_f32_e32 v41, v61
	v_mul_f32_e32 v38, v43, v39
	v_mul_f32_e32 v37, v37, v44
	v_mul_f32_e32 v38, v48, v38
	v_pk_add_f32 v[44:45], v[40:41], 1.0 op_sel_hi:[1,0]
	v_exp_f32_e32 v38, v38
	v_mul_f32_e32 v40, v44, v45
	v_rcp_f32_e32 v41, v40
	v_mul_f32_e32 v39, v42, v39
	v_fma_f32 v40, -v38, v38, 1.0
	v_max_f32_e32 v42, 0, v40
	v_mul_f32_e32 v40, v45, v41
	v_mul_f32_e32 v40, v48, v40
	v_exp_f32_e32 v40, v40
	v_sqrt_f32_e32 v45, v42
	v_exp_f32_e32 v42, v46
	v_exp_f32_e32 v43, v176
	v_fma_f32 v46, -v40, v40, 1.0
	s_waitcnt vmcnt(3)
	v_mfma_f32_32x32x16_bf16 v[2:17], v[70:73], v[4:7], 0
	v_max_f32_e32 v46, 0, v46
	v_sqrt_f32_e32 v49, v46
	v_pk_add_f32 v[46:47], v[42:43], 1.0 op_sel_hi:[1,0]
	v_mul_f32_e32 v39, v39, v45
	v_mul_f32_e32 v42, v46, v47
	v_rcp_f32_e32 v43, v42
	v_mul_f32_e32 v41, v44, v41
	v_exp_f32_e32 v44, v167
	v_exp_f32_e32 v45, v177
	v_mul_f32_e32 v42, v47, v43
	s_waitcnt vmcnt(2)
	v_mfma_f32_32x32x16_bf16 v[2:17], v[66:69], v[178:181], v[2:17]
	v_mul_f32_e32 v42, v48, v42
	v_add_f32_e64 v60, v44, 1.0
	v_add_f32_e64 v61, v45, 1.0
	v_exp_f32_e32 v42, v42
	v_mul_f32_e32 v44, v60, v61
	v_rcp_f32_e32 v45, v44
	v_mul_f32_e32 v43, v46, v43
	v_fma_f32 v44, -v42, v42, 1.0
	v_max_f32_e32 v46, 0, v44
	v_mul_f32_e32 v44, v61, v45
	v_mul_f32_e32 v44, v48, v44
	v_mfma_f32_32x32x16_bf16 v[18:33], v[78:81], v[182:185], v[18:33]
	v_exp_f32_e32 v44, v44
	v_fmamk_f32 v64, v64, 0xbfb8aa3b, v99
	v_mul_f32_e32 v41, v41, v49
	v_sqrt_f32_e32 v49, v46
	v_exp_f32_e32 v46, v168
	v_exp_f32_e32 v47, v64
	v_fma_f32 v61, -v44, v44, 1.0
	s_waitcnt vmcnt(1)
	v_mfma_f32_32x32x16_bf16 v[2:17], v[78:81], v[186:189], v[2:17]
	v_max_f32_e32 v61, 0, v61
	v_sqrt_f32_e32 v61, v61
	v_pk_add_f32 v[46:47], v[46:47], 1.0 op_sel_hi:[1,0]
	v_fmac_f32_e32 v99, 0xbfb8aa3b, v65
	v_mul_f32_e32 v64, v46, v47
	v_mul_f32_e32 v45, v60, v45
	v_rcp_f32_e32 v64, v64
	v_mfma_f32_32x32x16_bf16 v[18:33], v[74:77], v[170:173], v[18:33]
	v_mul_f32_e32 v45, v45, v61
	v_exp_f32_e32 v60, v97
	v_exp_f32_e32 v61, v99
	v_mul_f32_e32 v47, v47, v64
	v_mul_f32_e32 v43, v43, v49
	v_mul_f32_e32 v49, v46, v64
	v_pk_add_f32 v[60:61], v[60:61], 1.0 op_sel_hi:[1,0]
	s_waitcnt vmcnt(0)
; #define LAS __attribute__((address_space(3)))
; #define LDS_WAVE_SYNC() asm volatile("s_waitcnt lgkmcnt(0)" ::: "memory")
; template <int DIR, int MODE> ...
;     ...
;     for (int nt = 0; nt < 2; ++nt) {
;         const float nba = prm[DIR][nt][0], nbx = prm[DIR][nt][1], k8l = prm[DIR][nt][2];
; #pragma unroll
;         for (int i = 0; i < 16; ++i) {
;             const float d1 = 1.f + __builtin_amdgcn_exp2f(__builtin_fmaf(accR[nt][i], -1.4426950408889634f, nba));
;             const float d2 = 1.f + __builtin_amdgcn_exp2f(__builtin_fmaf(accI[nt][i], -1.4426950408889634f, nbx));
;             const float inv = __builtin_amdgcn_rcpf(d1 * d2), rr = inv * d2, ii = inv * d1;
;             const float av = __builtin_amdgcn_exp2f(k8l * rr);
;             accR[nt][i] = av; accI[nt][i] = __builtin_amdgcn_sqrtf(fmaxf(__builtin_fmaf(-av, av, 1.f), 0.f)) * ii; }
;     }
;     float hc = 0.f, ap = 1.f;
;     if (MODE == 1) hc = ((const float*)(a.ws + WS_CAR))[(size_t)((b * NCH + ch) * 2 + DIR) * LW + c];
; #pragma unroll
;     for (int hh = 0; hh < 2; ++hh) {
;         const int half = DIR == 0 ? hh : 1 - hh;
; #pragma unroll
;         for (int nt = 0; nt < 2; ++nt)
; #pragma unroll
;             for (int i = 0; i < 8; ++i) { const int tt = 8 * (i >> 2) + 4 * h + (i & 3);
;                 f32x2 v; v.x = accR[nt][8 * half + i]; v.y = accI[nt][8 * half + i];
;                 *(LAS f32x2*)(au + (tt * 64 + nt * 32 + r32) * 2) = v; }
;         LDS_WAVE_SYNC();
	v_mfma_f32_32x32x16_bf16 v[2:17], v[74:77], v[200:203], v[2:17]
	v_mul_f32_e32 v46, v48, v47
	v_mul_f32_e32 v47, v60, v61
	v_rcp_f32_e32 v97, v47
	v_fmamk_f32 v18, v18, 0xbfb8aa3b, v95
	v_exp_f32_e32 v46, v46
	v_exp_f32_e32 v64, v18
	v_mul_f32_e32 v61, v61, v97
	s_nop 4
	v_fmamk_f32 v2, v2, 0xbfb8aa3b, v93
	v_exp_f32_e32 v65, v2
	v_fma_f32 v47, -v46, v46, 1.0
	v_mul_f32_e32 v48, v48, v61
	v_max_f32_e32 v47, 0, v47
	v_pk_add_f32 v[64:65], v[64:65], 1.0 op_sel_hi:[1,0]
	v_exp_f32_e32 v48, v48
	v_mul_f32_e32 v18, v64, v65
	v_sqrt_f32_e32 v47, v47
	v_rcp_f32_e32 v193, v18
	v_fma_f32 v2, -v48, v48, 1.0
	v_mov_b32_e32 v125, v65
	v_mul_f32_e32 v47, v49, v47
	v_mul_f32_e32 v49, v60, v97
	v_max_f32_e32 v2, 0, v2
	v_pk_mul_f32 v[60:61], v[124:125], v[192:193]
	v_sqrt_f32_e32 v97, v2
	v_mul_f32_e32 v2, v60, v61
	v_exp_f32_e32 v2, v2
	v_fmamk_f32 v18, v19, 0xbfb8aa3b, v95
	v_fmamk_f32 v3, v3, 0xbfb8aa3b, v93
	v_exp_f32_e32 v18, v18
	v_exp_f32_e32 v19, v3
	v_fma_f32 v3, -v2, v2, 1.0
	v_max_f32_e32 v3, 0, v3
	v_sqrt_f32_e32 v3, v3
	v_pk_add_f32 v[18:19], v[18:19], 1.0 op_sel_hi:[1,0]
	v_mul_f32_e32 v64, v64, v193
	v_mul_f32_e32 v61, v18, v19
	v_rcp_f32_e32 v61, v61
	v_fmamk_f32 v20, v20, 0xbfb8aa3b, v95
	v_fmamk_f32 v4, v4, 0xbfb8aa3b, v93
	v_mul_f32_e32 v3, v64, v3
	v_exp_f32_e32 v64, v20
	v_exp_f32_e32 v65, v4
	v_mul_f32_e32 v19, v19, v61
	v_mul_f32_e32 v4, v60, v19
	v_mul_f32_e32 v20, v18, v61
	v_exp_f32_e32 v166, v4
	v_pk_add_f32 v[18:19], v[64:65], 1.0 op_sel_hi:[1,0]
	v_fmamk_f32 v5, v5, 0xbfb8aa3b, v93
	v_mul_f32_e32 v4, v18, v19
	v_rcp_f32_e32 v61, v4
	v_fma_f32 v4, -v166, v166, 1.0
	v_max_f32_e32 v4, 0, v4
	v_sqrt_f32_e32 v65, v4
	v_mul_f32_e32 v4, v19, v61
	v_mul_f32_e32 v4, v60, v4
	v_exp_f32_e32 v64, v4
	v_fmamk_f32 v4, v21, 0xbfb8aa3b, v95
	v_exp_f32_e32 v4, v4
	v_exp_f32_e32 v5, v5
	v_fma_f32 v19, -v64, v64, 1.0
	v_max_f32_e32 v19, 0, v19
	v_sqrt_f32_e32 v19, v19
	v_pk_add_f32 v[4:5], v[4:5], 1.0 op_sel_hi:[1,0]
	v_mul_f32_e32 v49, v49, v97
	v_mul_f32_e32 v21, v4, v5
	v_rcp_f32_e32 v97, v21
	v_mul_f32_e32 v18, v18, v61
	v_mul_f32_e32 v167, v20, v65
	v_mul_f32_e32 v65, v18, v19
	v_fmamk_f32 v18, v22, 0xbfb8aa3b, v95
	v_fmamk_f32 v6, v6, 0xbfb8aa3b, v93
	v_exp_f32_e32 v20, v18
	v_exp_f32_e32 v21, v6
	v_mul_f32_e32 v5, v5, v97
	v_mul_f32_e32 v19, v4, v97
	v_mul_f32_e32 v4, v60, v5
	v_exp_f32_e32 v18, v4
	v_pk_add_f32 v[4:5], v[20:21], 1.0 op_sel_hi:[1,0]
	v_fmamk_f32 v9, v9, 0xbfb8aa3b, v93
	v_mul_f32_e32 v6, v4, v5
	v_rcp_f32_e32 v61, v6
	v_fma_f32 v6, -v18, v18, 1.0
	v_max_f32_e32 v6, 0, v6
	v_sqrt_f32_e32 v22, v6
	v_mul_f32_e32 v5, v5, v61
	v_mul_f32_e32 v5, v60, v5
	v_fmamk_f32 v6, v23, 0xbfb8aa3b, v95
	v_exp_f32_e32 v20, v6
	v_exp_f32_e32 v6, v5
	v_fmamk_f32 v5, v7, 0xbfb8aa3b, v93
	v_exp_f32_e32 v21, v5
	v_mul_f32_e32 v19, v19, v22
	v_fma_f32 v5, -v6, v6, 1.0
	v_max_f32_e32 v5, 0, v5
	v_pk_add_f32 v[20:21], v[20:21], 1.0 op_sel_hi:[1,0]
	v_sqrt_f32_e32 v5, v5
	v_mul_f32_e32 v7, v20, v21
	v_rcp_f32_e32 v97, v7
	v_fmamk_f32 v7, v24, 0xbfb8aa3b, v95
	v_exp_f32_e32 v22, v7
	v_fmamk_f32 v7, v8, 0xbfb8aa3b, v93
	v_exp_f32_e32 v23, v7
	v_mul_f32_e32 v4, v4, v61
	v_mul_f32_e32 v7, v4, v5
	v_mul_f32_e32 v8, v21, v97
	v_pk_add_f32 v[4:5], v[22:23], 1.0 op_sel_hi:[1,0]
	v_mul_f32_e32 v8, v60, v8
	v_mul_f32_e32 v21, v4, v5
	v_rcp_f32_e32 v21, v21
	v_mul_f32_e32 v24, v20, v97
	v_exp_f32_e32 v8, v8
	v_exp_f32_e32 v23, v9
	v_mul_f32_e32 v5, v5, v21
	v_mul_f32_e32 v5, v60, v5
	v_exp_f32_e32 v20, v5
	v_fma_f32 v5, -v8, v8, 1.0
	v_max_f32_e32 v5, 0, v5
	v_sqrt_f32_e32 v5, v5
	v_fma_f32 v22, -v20, v20, 1.0
	v_max_f32_e32 v22, 0, v22
	v_sqrt_f32_e32 v61, v22
	v_fmamk_f32 v22, v25, 0xbfb8aa3b, v95
	v_exp_f32_e32 v22, v22
	v_mul_f32_e32 v4, v4, v21
	v_mul_f32_e32 v9, v24, v5
	v_mul_f32_e32 v21, v4, v61
	v_pk_add_f32 v[4:5], v[22:23], 1.0 op_sel_hi:[1,0]
	v_lshlrev_b32_e32 v23, 11, v165
	v_lshlrev_b32_e32 v24, 3, v164
	v_mul_f32_e32 v22, v4, v5
	v_add3_u32 v24, s0, v23, v24
	v_rcp_f32_e32 v22, v22
	v_add_u32_e32 v124, 0x1000, v24
	ds_write2_b64 v124, v[128:129], v[2:3] offset0:64 offset1:96
	v_fmamk_f32 v2, v26, 0xbfb8aa3b, v95
	v_fmamk_f32 v3, v10, 0xbfb8aa3b, v93
	v_exp_f32_e32 v2, v2
	v_exp_f32_e32 v3, v3
	v_mul_f32_e32 v5, v5, v22
	v_mul_f32_e32 v5, v60, v5
	v_exp_f32_e32 v10, v5
	v_mul_f32_e32 v25, v4, v22
	v_pk_add_f32 v[4:5], v[2:3], 1.0 op_sel_hi:[1,0]
	v_fmamk_f32 v13, v13, 0xbfb8aa3b, v93
	v_mul_f32_e32 v2, v4, v5
	v_rcp_f32_e32 v3, v2
	v_fma_f32 v2, -v10, v10, 1.0
	v_max_f32_e32 v2, 0, v2
	v_sqrt_f32_e32 v61, v2
	v_mul_f32_e32 v2, v5, v3
	v_fmamk_f32 v5, v27, 0xbfb8aa3b, v95
	v_mul_f32_e32 v2, v60, v2
	v_exp_f32_e32 v22, v5
	v_fmamk_f32 v5, v11, 0xbfb8aa3b, v93
	v_exp_f32_e32 v2, v2
	v_exp_f32_e32 v23, v5
	v_mul_f32_e32 v3, v4, v3
	v_fmamk_f32 v14, v14, 0xbfb8aa3b, v93
	v_fma_f32 v5, -v2, v2, 1.0
	v_pk_add_f32 v[26:27], v[22:23], 1.0 op_sel_hi:[1,0]
	v_max_f32_e32 v5, 0, v5
	v_mul_f32_e32 v11, v26, v27
	v_sqrt_f32_e32 v5, v5
	v_rcp_f32_e32 v97, v11
	v_mul_f32_e32 v11, v25, v61
	ds_write2_b64 v124, v[126:127], v[166:167] offset0:128 offset1:160
	v_mul_f32_e32 v3, v3, v5
	v_mul_f32_e32 v4, v27, v97
	v_fmamk_f32 v5, v28, 0xbfb8aa3b, v95
	v_mul_f32_e32 v4, v60, v4
	v_exp_f32_e32 v22, v5
	v_fmamk_f32 v5, v12, 0xbfb8aa3b, v93
	v_exp_f32_e32 v4, v4
	v_exp_f32_e32 v23, v5
	v_exp_f32_e32 v27, v13
	v_add_u32_e32 v126, 0x1800, v24
	v_fma_f32 v5, -v4, v4, 1.0
	v_pk_add_f32 v[22:23], v[22:23], 1.0 op_sel_hi:[1,0]
	v_max_f32_e32 v5, 0, v5
	v_mul_f32_e32 v12, v22, v23
	v_sqrt_f32_e32 v5, v5
	v_rcp_f32_e32 v25, v12
	v_mul_f32_e32 v12, v26, v97
	ds_write2_b64 v126, v[54:55], v[18:19] offset1:32
	v_mul_f32_e32 v5, v12, v5
	v_mul_f32_e32 v12, v23, v25
	v_fmamk_f32 v23, v29, 0xbfb8aa3b, v95
	v_exp_f32_e32 v26, v23
	v_mul_f32_e32 v12, v60, v12
	v_exp_f32_e32 v12, v12
	v_mul_f32_e32 v22, v22, v25
	v_pk_add_f32 v[26:27], v[26:27], 1.0 op_sel_hi:[1,0]
	v_exp_f32_e32 v29, v14
	v_mul_f32_e32 v23, v26, v27
	v_fma_f32 v13, -v12, v12, 1.0
	v_rcp_f32_e32 v28, v23
	v_max_f32_e32 v13, 0, v13
	v_sqrt_f32_e32 v13, v13
	v_fmamk_f32 v18, v31, 0xbfb8aa3b, v95
	v_mul_f32_e32 v23, v27, v28
	v_mul_f32_e32 v23, v60, v23
	v_mul_f32_e32 v13, v22, v13
	v_mul_f32_e32 v22, v26, v28
	v_exp_f32_e32 v26, v23
	v_fmamk_f32 v23, v30, 0xbfb8aa3b, v95
	v_exp_f32_e32 v28, v23
	v_fmamk_f32 v15, v15, 0xbfb8aa3b, v93
	v_fma_f32 v14, -v26, v26, 1.0
	v_max_f32_e32 v14, 0, v14
	v_pk_add_f32 v[28:29], v[28:29], 1.0 op_sel_hi:[1,0]
	v_exp_f32_e32 v18, v18
	v_mul_f32_e32 v23, v28, v29
	v_exp_f32_e32 v19, v15
	v_sqrt_f32_e32 v14, v14
	v_rcp_f32_e32 v23, v23
	v_add_u32_e32 v127, 0x2000, v24
	v_add_u32_e32 v128, 0x2800, v24
	ds_write2_b64 v124, v[62:63], v[64:65] offset0:192 offset1:224
	ds_write2_b64 v127, v[50:51], v[6:7] offset0:64 offset1:96
	ds_write2_b64 v127, v[52:53], v[8:9] offset0:128 offset1:160
	ds_write2_b64 v127, v[56:57], v[20:21] offset0:192 offset1:224
	ds_write2_b64 v128, v[58:59], v[10:11] offset1:32
	v_lshl_add_u32 v125, v84, 3, s0
	v_pk_add_f32 v[18:19], v[18:19], 1.0 op_sel_hi:[1,0]
	s_waitcnt lgkmcnt(0)
; __device__ __forceinline__ unsigned cvt_pk_bf16(float lo, float hi) { unsigned r; asm volatile("v_cvt_pk_bf16_f32 %0, %1, %2" : "=v"(r) : "v"(lo), "v"(hi)); return r; }
; #define LAS __attribute__((address_space(3)))
; #define LDS_WAVE_SYNC() asm volatile("s_waitcnt lgkmcnt(0)" ::: "memory")
; template <int DIR, int MODE> ...
;     ...
;             const float d1 = 1.f + __builtin_amdgcn_exp2f(__builtin_fmaf(accR[nt][i], -1.4426950408889634f, nba));
;             const float d2 = 1.f + __builtin_amdgcn_exp2f(__builtin_fmaf(accI[nt][i], -1.4426950408889634f, nbx));
;             const float inv = __builtin_amdgcn_rcpf(d1 * d2), rr = inv * d2, ii = inv * d1;
;             const float av = __builtin_amdgcn_exp2f(k8l * rr);
;             accR[nt][i] = av; accI[nt][i] = __builtin_amdgcn_sqrtf(fmaxf(__builtin_fmaf(-av, av, 1.f), 0.f)) * ii; }
;     ...
;             for (int i = 0; i < 8; ++i) { const int tt = 8 * (i >> 2) + 4 * h + (i & 3);
;                 f32x2 v; v.x = accR[nt][8 * half + i]; v.y = accI[nt][8 * half + i];
;                 *(LAS f32x2*)(au + (tt * 64 + nt * 32 + r32) * 2) = v; }
;         LDS_WAVE_SYNC();
; #pragma unroll
;         for (int s = 0; s < 16; ++s) {
;             const int tt = DIR == 0 ? s : 15 - s, t = half * 16 + tt;
;             const f32x2 v = *(const LAS f32x2*)(au + (tt * 64 + lane) * 2);
;             hc = v.x * hc + v.y * xcr[t];
;             if (MODE == 0) { ap *= v.x;
;                 ((unsigned*)(a.ws + WS_HP))[((size_t)DIR * T + (size_t)b * SEQ + ch * 32 + t) * LW + c] = pg8::cvt_pk_bf16(hc, ap); }
;             if (MODE == 1) { if (DIR == 0) hf[t] = hc; else hf[t] = gl[t] * (hf[t] + hc); }
;         }
	v_mul_f32_e32 v27, v22, v14
	v_mul_f32_e32 v14, v29, v23
	v_mul_f32_e32 v22, v28, v23
	v_mul_f32_e32 v23, v18, v19
	ds_read_b64 v[8:9], v125 offset:4608
	v_rcp_f32_e32 v23, v23
	v_mov_b32_e32 v84, v1
	v_mul_f32_e32 v14, v60, v14
	v_exp_f32_e32 v14, v14
	v_mul_f32_e32 v7, v18, v23
	s_waitcnt lgkmcnt(0)
	v_mul_f32_e32 v18, v85, v9
	v_mul_f32_e32 v6, v19, v23
	v_pk_fma_f32 v[18:19], v[84:85], v[8:9], v[18:19] op_sel_hi:[1,1,0]
	v_fma_f32 v15, -v14, v14, 1.0
	v_cvt_pk_bf16_f32 v19, v18, v8
	ds_read_b64 v[20:21], v125 offset:5120
	v_mul_f32_e32 v6, v60, v6
	v_max_f32_e32 v15, 0, v15
	v_exp_f32_e32 v6, v6
	v_fmamk_f32 v11, v16, 0xbfb8aa3b, v93
	global_store_dword v[122:123], v19, off
	v_mov_b32_e32 v19, v0
	s_waitcnt lgkmcnt(0)
	v_mul_f32_e32 v16, v0, v21
	v_sqrt_f32_e32 v15, v15
	v_pk_fma_f32 v[18:19], v[18:19], v[20:21], v[16:17] op_sel_hi:[1,1,0]
	v_pk_mul_f32 v[8:9], v[8:9], v[20:21]
	v_fma_f32 v10, -v6, v6, 1.0
	v_cvt_pk_bf16_f32 v16, v18, v8
	ds_read_b64 v[20:21], v125 offset:5632
	v_mul_f32_e32 v15, v22, v15
	v_max_f32_e32 v22, 0, v10
	v_fmamk_f32 v10, v32, 0xbfb8aa3b, v95
	v_exp_f32_e32 v10, v10
	v_exp_f32_e32 v11, v11
	global_store_dword v[120:121], v16, off offset:2048
	v_mov_b32_e32 v19, v130
	s_waitcnt lgkmcnt(0)
	v_mul_f32_e32 v16, v130, v21
	v_pk_fma_f32 v[18:19], v[18:19], v[20:21], v[16:17] op_sel_hi:[1,1,0]
	v_pk_mul_f32 v[8:9], v[8:9], v[20:21]
	v_pk_add_f32 v[10:11], v[10:11], 1.0 op_sel_hi:[1,0]
	v_cvt_pk_bf16_f32 v16, v18, v8
	ds_read_b64 v[20:21], v125 offset:6144
	v_mul_f32_e32 v19, v10, v11
	v_rcp_f32_e32 v23, v19
	global_store_dword v[116:117], v16, off offset:-4096
	v_mov_b32_e32 v19, v131
	s_waitcnt lgkmcnt(0)
	v_mul_f32_e32 v16, v131, v21
	v_pk_fma_f32 v[18:19], v[18:19], v[20:21], v[16:17] op_sel_hi:[1,1,0]
	v_pk_mul_f32 v[8:9], v[8:9], v[20:21]
	v_mov_b32_e32 v19, v132
	v_cvt_pk_bf16_f32 v16, v18, v8
	ds_read_b64 v[20:21], v125 offset:6656
	global_store_dword v[118:119], v16, off offset:2048
	v_sqrt_f32_e32 v22, v22
	v_mul_f32_e32 v11, v11, v23
	v_mul_f32_e32 v11, v60, v11
	s_waitcnt lgkmcnt(0)
	v_mul_f32_e32 v16, v132, v21
	v_pk_fma_f32 v[18:19], v[18:19], v[20:21], v[16:17] op_sel_hi:[1,1,0]
	v_pk_mul_f32 v[8:9], v[8:9], v[20:21]
	v_mul_f32_e32 v7, v7, v22
	v_cvt_pk_bf16_f32 v19, v18, v8
	ds_read_b64 v[20:21], v125 offset:7168
	global_store_dword v[116:117], v19, off
	v_mov_b32_e32 v19, v133
	v_exp_f32_e32 v16, v11
	v_fmac_f32_e32 v95, 0xbfb8aa3b, v33
	s_waitcnt lgkmcnt(0)
	v_mul_f32_e32 v22, v133, v21
	v_pk_fma_f32 v[18:19], v[18:19], v[20:21], v[22:23] op_sel_hi:[1,1,0]
	v_pk_mul_f32 v[8:9], v[8:9], v[20:21]
	v_mul_f32_e32 v23, v10, v23
	v_cvt_pk_bf16_f32 v11, v18, v8
	ds_read_b64 v[20:21], v125 offset:7680
	v_mov_b32_e32 v19, v134
	global_store_dword v[116:117], v11, off offset:2048
	v_fmac_f32_e32 v93, 0xbfb8aa3b, v17
	v_add_co_u32_e32 v110, vcc, s1, v88
	s_waitcnt lgkmcnt(0)
	v_mul_f32_e32 v10, v134, v21
	v_pk_fma_f32 v[10:11], v[18:19], v[20:21], v[10:11] op_sel_hi:[1,1,0]
	v_pk_mul_f32 v[8:9], v[8:9], v[20:21]
	v_exp_f32_e32 v20, v95
	v_cvt_pk_bf16_f32 v11, v10, v8
	ds_read_b64 v[18:19], v125 offset:8192
	global_store_dword v[112:113], v11, off offset:-4096
	v_mov_b32_e32 v11, v135
	v_exp_f32_e32 v21, v93
	v_addc_co_u32_e32 v111, vcc, 0, v89, vcc
	s_waitcnt lgkmcnt(0)
	v_mul_f32_e32 v22, v135, v19
	v_pk_fma_f32 v[10:11], v[10:11], v[18:19], v[22:23] op_sel_hi:[1,1,0]
	v_pk_mul_f32 v[8:9], v[8:9], v[18:19]
	v_pk_add_f32 v[20:21], v[20:21], 1.0 op_sel_hi:[1,0]
	v_cvt_pk_bf16_f32 v11, v10, v8
	ds_read_b64 v[18:19], v125 offset:8704
	global_store_dword v[114:115], v11, off offset:2048
	v_mov_b32_e32 v11, v136
	s_mov_b32 s1, 0x11f06000
	v_add_co_u32_e32 v108, vcc, s1, v88
	s_waitcnt lgkmcnt(0)
	v_mul_f32_e32 v22, v136, v19
	v_pk_fma_f32 v[10:11], v[10:11], v[18:19], v[22:23] op_sel_hi:[1,1,0]
	v_pk_mul_f32 v[8:9], v[8:9], v[18:19]
	v_addc_co_u32_e32 v109, vcc, 0, v89, vcc
	v_cvt_pk_bf16_f32 v11, v10, v8
	ds_read_b64 v[18:19], v125 offset:9216
	global_store_dword v[112:113], v11, off
	v_mov_b32_e32 v11, v137
	v_fma_f32 v24, -v16, v16, 1.0
	v_max_f32_e32 v17, 0, v24
	s_waitcnt lgkmcnt(0)
	v_mul_f32_e32 v22, v137, v19
	v_pk_fma_f32 v[10:11], v[10:11], v[18:19], v[22:23] op_sel_hi:[1,1,0]
	v_pk_mul_f32 v[8:9], v[8:9], v[18:19]
	v_mul_f32_e32 v22, v20, v21
	v_cvt_pk_bf16_f32 v11, v10, v8
	ds_read_b64 v[18:19], v125 offset:9728
	v_rcp_f32_e32 v25, v22
	global_store_dword v[112:113], v11, off offset:2048
	v_mov_b32_e32 v11, v138
	s_mov_b32 s1, 0x11f07000
	s_waitcnt lgkmcnt(0)
	v_mul_f32_e32 v22, v138, v19
	v_pk_fma_f32 v[10:11], v[10:11], v[18:19], v[22:23] op_sel_hi:[1,1,0]
	v_pk_mul_f32 v[8:9], v[8:9], v[18:19]
	v_mul_f32_e32 v21, v21, v25
	v_cvt_pk_bf16_f32 v11, v10, v8
	ds_read_b64 v[18:19], v125 offset:10240
	global_store_dword v[108:109], v11, off offset:-4096
	v_mov_b32_e32 v11, v139
	v_mul_f32_e32 v21, v60, v21
	v_add_co_u32_e32 v106, vcc, s1, v88
	s_waitcnt lgkmcnt(0)
	v_mul_f32_e32 v22, v139, v19
	v_pk_fma_f32 v[10:11], v[10:11], v[18:19], v[22:23] op_sel_hi:[1,1,0]
	v_pk_mul_f32 v[8:9], v[8:9], v[18:19]
	v_exp_f32_e32 v22, v21
	v_cvt_pk_bf16_f32 v11, v10, v8
	ds_read_b64 v[18:19], v125 offset:10752
	global_store_dword v[110:111], v11, off offset:2048
	v_mov_b32_e32 v11, v140
	v_fma_f32 v21, -v22, v22, 1.0
	v_max_f32_e32 v21, 0, v21
	s_waitcnt lgkmcnt(0)
	v_mul_f32_e32 v24, v140, v19
	v_pk_fma_f32 v[10:11], v[10:11], v[18:19], v[24:25] op_sel_hi:[1,1,0]
	v_pk_mul_f32 v[8:9], v[8:9], v[18:19]
	v_sqrt_f32_e32 v17, v17
	v_cvt_pk_bf16_f32 v11, v10, v8
	ds_read_b64 v[18:19], v125 offset:11264
	global_store_dword v[108:109], v11, off
	v_mov_b32_e32 v11, v141
	v_sqrt_f32_e32 v21, v21
	v_addc_co_u32_e32 v107, vcc, 0, v89, vcc
	s_waitcnt lgkmcnt(0)
; __device__ __forceinline__ unsigned cvt_pk_bf16(float lo, float hi) { unsigned r; asm volatile("v_cvt_pk_bf16_f32 %0, %1, %2" : "=v"(r) : "v"(lo), "v"(hi)); return r; }
; #define LAS __attribute__((address_space(3)))
; #define LDS_WAVE_SYNC() asm volatile("s_waitcnt lgkmcnt(0)" ::: "memory")
; template <int DIR, int MODE> ...
;     ...
;     for (int hh = 0; hh < 2; ++hh) {
;         const int half = DIR == 0 ? hh : 1 - hh;
; #pragma unroll
;         for (int nt = 0; nt < 2; ++nt)
; #pragma unroll
;             for (int i = 0; i < 8; ++i) { const int tt = 8 * (i >> 2) + 4 * h + (i & 3);
;                 f32x2 v; v.x = accR[nt][8 * half + i]; v.y = accI[nt][8 * half + i];
;                 *(LAS f32x2*)(au + (tt * 64 + nt * 32 + r32) * 2) = v; }
;         LDS_WAVE_SYNC();
; #pragma unroll
;         for (int s = 0; s < 16; ++s) {
;             const int tt = DIR == 0 ? s : 15 - s, t = half * 16 + tt;
;             const f32x2 v = *(const LAS f32x2*)(au + (tt * 64 + lane) * 2);
;             hc = v.x * hc + v.y * xcr[t];
;             if (MODE == 0) { ap *= v.x;
;                 ((unsigned*)(a.ws + WS_HP))[((size_t)DIR * T + (size_t)b * SEQ + ch * 32 + t) * LW + c] = pg8::cvt_pk_bf16(hc, ap); }
;             if (MODE == 1) { if (DIR == 0) hf[t] = hc; else hf[t] = gl[t] * (hf[t] + hc); }
;         }
;         LDS_WAVE_SYNC();
	v_mul_f32_e32 v24, v141, v19
	v_pk_fma_f32 v[10:11], v[10:11], v[18:19], v[24:25] op_sel_hi:[1,1,0]
	v_pk_mul_f32 v[8:9], v[8:9], v[18:19]
	s_mov_b32 s1, 0x11f08000
	v_cvt_pk_bf16_f32 v11, v10, v8
	ds_read_b64 v[18:19], v125 offset:11776
	global_store_dword v[108:109], v11, off offset:2048
	v_mov_b32_e32 v11, v142
	v_add_co_u32_e32 v104, vcc, s1, v88
	s_waitcnt lgkmcnt(0)
	v_mul_f32_e32 v24, v142, v19
	v_pk_fma_f32 v[10:11], v[10:11], v[18:19], v[24:25] op_sel_hi:[1,1,0]
	v_pk_mul_f32 v[8:9], v[8:9], v[18:19]
	v_addc_co_u32_e32 v105, vcc, 0, v89, vcc
	v_cvt_pk_bf16_f32 v11, v10, v8
	ds_read_b64 v[18:19], v125 offset:12288
	v_mul_f32_e32 v20, v20, v25
	v_mul_f32_e32 v17, v23, v17
	v_mul_f32_e32 v23, v20, v21
	global_store_dword v[104:105], v11, off offset:-4096
	v_mov_b32_e32 v11, v143
	s_waitcnt lgkmcnt(0)
	v_mul_f32_e32 v20, v143, v19
	v_pk_fma_f32 v[10:11], v[10:11], v[18:19], v[20:21] op_sel_hi:[1,1,0]
	v_pk_mul_f32 v[8:9], v[8:9], v[18:19]
	v_cvt_pk_bf16_f32 v11, v10, v8
	global_store_dword v[106:107], v11, off offset:2048
	s_waitcnt lgkmcnt(0)
	ds_write2_b64 v124, v[34:35], v[2:3] offset0:64 offset1:96
	ds_write2_b64 v124, v[36:37], v[4:5] offset0:128 offset1:160
	ds_write2_b64 v124, v[38:39], v[12:13] offset0:192 offset1:224
	ds_write2_b64 v126, v[40:41], v[26:27] offset1:32
	ds_write2_b64 v127, v[42:43], v[14:15] offset0:64 offset1:96
	ds_write2_b64 v127, v[44:45], v[6:7] offset0:128 offset1:160
	ds_write2_b64 v127, v[46:47], v[16:17] offset0:192 offset1:224
	ds_write2_b64 v128, v[48:49], v[22:23] offset1:32
	s_waitcnt lgkmcnt(0)
	ds_read_b64 v[2:3], v125 offset:4608
	v_mov_b32_e32 v11, v144
	s_mov_b32 s1, 0x11f0a000
	s_waitcnt lgkmcnt(0)
	v_mul_f32_e32 v6, v144, v3
	v_pk_fma_f32 v[6:7], v[10:11], v[2:3], v[6:7] op_sel_hi:[1,1,0]
	v_pk_mul_f32 v[2:3], v[8:9], v[2:3]
	v_cvt_pk_bf16_f32 v7, v6, v2
	ds_read_b64 v[8:9], v125 offset:5120
	global_store_dword v[104:105], v7, off
	v_mov_b32_e32 v7, v145
	v_add_co_u32_e32 v10, vcc, s1, v88
	s_waitcnt lgkmcnt(0)
	v_mul_f32_e32 v4, v145, v9
	v_pk_fma_f32 v[6:7], v[6:7], v[8:9], v[4:5] op_sel_hi:[1,1,0]
	v_pk_mul_f32 v[2:3], v[2:3], v[8:9]
	v_mov_b32_e32 v7, v146
	v_cvt_pk_bf16_f32 v4, v6, v2
	ds_read_b64 v[8:9], v125 offset:5632
	global_store_dword v[104:105], v4, off offset:2048
	v_addc_co_u32_e32 v11, vcc, 0, v89, vcc
	s_mov_b32 s0, 0x11f09000
	s_waitcnt lgkmcnt(0)
	v_mul_f32_e32 v4, v146, v9
	v_pk_fma_f32 v[6:7], v[6:7], v[8:9], v[4:5] op_sel_hi:[1,1,0]
	v_pk_mul_f32 v[2:3], v[2:3], v[8:9]
	v_mov_b32_e32 v7, v147
	v_cvt_pk_bf16_f32 v4, v6, v2
	ds_read_b64 v[8:9], v125 offset:6144
	global_store_dword v[10:11], v4, off offset:-4096
	v_add_co_u32_e32 v12, vcc, s0, v88
	s_mov_b32 s1, 0x11f0c000
	s_waitcnt lgkmcnt(0)
	v_mul_f32_e32 v4, v147, v9
	v_pk_fma_f32 v[6:7], v[6:7], v[8:9], v[4:5] op_sel_hi:[1,1,0]
	v_pk_mul_f32 v[2:3], v[2:3], v[8:9]
	v_addc_co_u32_e32 v13, vcc, 0, v89, vcc
	v_cvt_pk_bf16_f32 v4, v6, v2
	ds_read_b64 v[8:9], v125 offset:6656
	global_store_dword v[12:13], v4, off offset:2048
	v_mov_b32_e32 v7, v148
	s_mov_b32 s0, 0x11f0b000
	s_waitcnt lgkmcnt(0)
	v_mul_f32_e32 v4, v148, v9
	v_pk_fma_f32 v[6:7], v[6:7], v[8:9], v[4:5] op_sel_hi:[1,1,0]
	v_pk_mul_f32 v[2:3], v[2:3], v[8:9]
	v_cvt_pk_bf16_f32 v4, v6, v2
	ds_read_b64 v[8:9], v125 offset:7168
	global_store_dword v[10:11], v4, off
	v_mov_b32_e32 v7, v149
	s_waitcnt lgkmcnt(0)
	v_mul_f32_e32 v4, v149, v9
	v_pk_fma_f32 v[4:5], v[6:7], v[8:9], v[4:5] op_sel_hi:[1,1,0]
	v_pk_mul_f32 v[2:3], v[2:3], v[8:9]
	s_nop 0
	v_cvt_pk_bf16_f32 v5, v4, v2
	ds_read_b64 v[6:7], v125 offset:7680
	global_store_dword v[10:11], v5, off offset:2048
	v_mov_b32_e32 v5, v150
	s_waitcnt lgkmcnt(0)
	v_mul_f32_e32 v8, v150, v7
	v_pk_fma_f32 v[4:5], v[4:5], v[6:7], v[8:9] op_sel_hi:[1,1,0]
	v_pk_mul_f32 v[2:3], v[2:3], v[6:7]
	v_add_co_u32_e32 v8, vcc, s1, v88
	v_cvt_pk_bf16_f32 v5, v4, v2
	ds_read_b64 v[6:7], v125 offset:8192
	s_nop 0
	v_addc_co_u32_e32 v9, vcc, 0, v89, vcc
	global_store_dword v[8:9], v5, off offset:-4096
	v_mov_b32_e32 v5, v151
	s_waitcnt lgkmcnt(0)
	v_mul_f32_e32 v10, v151, v7
	v_pk_fma_f32 v[4:5], v[4:5], v[6:7], v[10:11] op_sel_hi:[1,1,0]
	v_pk_mul_f32 v[2:3], v[2:3], v[6:7]
	v_add_co_u32_e32 v10, vcc, s0, v88
	v_cvt_pk_bf16_f32 v5, v4, v2
	ds_read_b64 v[6:7], v125 offset:8704
	s_nop 0
	v_addc_co_u32_e32 v11, vcc, 0, v89, vcc
	global_store_dword v[10:11], v5, off offset:2048
	v_mov_b32_e32 v5, v152
	s_waitcnt lgkmcnt(0)
	v_mul_f32_e32 v10, v152, v7
	v_pk_fma_f32 v[4:5], v[4:5], v[6:7], v[10:11] op_sel_hi:[1,1,0]
	v_pk_mul_f32 v[2:3], v[2:3], v[6:7]
	v_cvt_pk_bf16_f32 v5, v4, v2
	ds_read_b64 v[6:7], v125 offset:9216
	global_store_dword v[8:9], v5, off
	v_mov_b32_e32 v5, v153
	s_mov_b32 s1, 0x11f0e000
	s_waitcnt lgkmcnt(0)
	v_mul_f32_e32 v10, v153, v7
	v_pk_fma_f32 v[4:5], v[4:5], v[6:7], v[10:11] op_sel_hi:[1,1,0]
	v_pk_mul_f32 v[2:3], v[2:3], v[6:7]
	s_mov_b32 s0, 0x11f0d000
	v_cvt_pk_bf16_f32 v5, v4, v2
	ds_read_b64 v[6:7], v125 offset:9728
	global_store_dword v[8:9], v5, off offset:2048
	v_mov_b32_e32 v5, v154
	s_waitcnt lgkmcnt(0)
	v_mul_f32_e32 v8, v154, v7
	v_pk_fma_f32 v[4:5], v[4:5], v[6:7], v[8:9] op_sel_hi:[1,1,0]
	v_pk_mul_f32 v[2:3], v[2:3], v[6:7]
	v_add_co_u32_e32 v8, vcc, s1, v88
	v_cvt_pk_bf16_f32 v5, v4, v2
	ds_read_b64 v[6:7], v125 offset:10240
	s_nop 0
	v_addc_co_u32_e32 v9, vcc, 0, v89, vcc
	global_store_dword v[8:9], v5, off offset:-4096
	v_mov_b32_e32 v5, v155
	s_waitcnt lgkmcnt(0)
	v_mul_f32_e32 v10, v155, v7
	v_pk_fma_f32 v[4:5], v[4:5], v[6:7], v[10:11] op_sel_hi:[1,1,0]
	v_pk_mul_f32 v[2:3], v[2:3], v[6:7]
	v_add_co_u32_e32 v10, vcc, s0, v88
	v_cvt_pk_bf16_f32 v5, v4, v2
	ds_read_b64 v[6:7], v125 offset:10752
	s_nop 0
	v_addc_co_u32_e32 v11, vcc, 0, v89, vcc
	global_store_dword v[10:11], v5, off offset:2048
	v_mov_b32_e32 v5, v156
	s_waitcnt lgkmcnt(0)
; __device__ __forceinline__ unsigned cvt_pk_bf16(float lo, float hi) { unsigned r; asm volatile("v_cvt_pk_bf16_f32 %0, %1, %2" : "=v"(r) : "v"(lo), "v"(hi)); return r; }
; #define LAS __attribute__((address_space(3)))
; #define MFMA32(a, b, c) __builtin_amdgcn_mfma_f32_32x32x16_bf16((a), (b), (c), 0, 0, 0)
; #define LDS_WAVE_SYNC() asm volatile("s_waitcnt lgkmcnt(0)" ::: "memory")
; template <int DIR, int MODE> ...
;     ...
;         const bf16* wr_ = wl + (size_t)((DIR * 8 + w) * 2) * 4096 + (nt * 32 + r32) * 64 + 8 * h;
; #pragma unroll
;         for (int ks = 0; ks < 4; ++ks) {
;             const bf16x8 bR = *(const bf16x8*)(wr_ + 16 * ks), bI = *(const bf16x8*)(wr_ + 4096 + 16 * ks);
;             accR[nt] = MFMA32(af[ks], bR, accR[nt]); accI[nt] = MFMA32(af[ks], bI, accI[nt]); }
;     }
; #pragma unroll
;     for (int nt = 0; nt < 2; ++nt) {
;         const float nba = prm[DIR][nt][0], nbx = prm[DIR][nt][1], k8l = prm[DIR][nt][2];
; #pragma unroll
;         for (int i = 0; i < 16; ++i) {
;             const float d1 = 1.f + __builtin_amdgcn_exp2f(__builtin_fmaf(accR[nt][i], -1.4426950408889634f, nba));
;             const float d2 = 1.f + __builtin_amdgcn_exp2f(__builtin_fmaf(accI[nt][i], -1.4426950408889634f, nbx));
;             const float inv = __builtin_amdgcn_rcpf(d1 * d2), rr = inv * d2, ii = inv * d1;
;             const float av = __builtin_amdgcn_exp2f(k8l * rr);
;             accR[nt][i] = av; accI[nt][i] = __builtin_amdgcn_sqrtf(fmaxf(__builtin_fmaf(-av, av, 1.f), 0.f)) * ii; }
;     ...
;         for (int s = 0; s < 16; ++s) {
;             const int tt = DIR == 0 ? s : 15 - s, t = half * 16 + tt;
;             const f32x2 v = *(const LAS f32x2*)(au + (tt * 64 + lane) * 2);
;             hc = v.x * hc + v.y * xcr[t];
;             if (MODE == 0) { ap *= v.x;
;                 ((unsigned*)(a.ws + WS_HP))[((size_t)DIR * T + (size_t)b * SEQ + ch * 32 + t) * LW + c] = pg8::cvt_pk_bf16(hc, ap); }
;             if (MODE == 1) { if (DIR == 0) hf[t] = hc; else hf[t] = gl[t] * (hf[t] + hc); }
;         }
;         LDS_WAVE_SYNC();
;     }
;     if (MODE == 0) { f32x2 v; v.x = ap; v.y = hc; ((f32x2*)(a.ws + WS_TOT))[(size_t)((b * NCH + ch) * 2 + DIR) * LW + c] = v; }
	v_mul_f32_e32 v10, v156, v7
	v_pk_fma_f32 v[4:5], v[4:5], v[6:7], v[10:11] op_sel_hi:[1,1,0]
	v_pk_mul_f32 v[2:3], v[2:3], v[6:7]
	s_mov_b32 s0, 0x11f0f000
	v_cvt_pk_bf16_f32 v5, v4, v2
	ds_read_b64 v[6:7], v125 offset:11264
	global_store_dword v[8:9], v5, off
	v_mov_b32_e32 v5, v157
	v_lshl_add_u64 v[10:11], s[42:43], 0, v[82:83]
	s_waitcnt lgkmcnt(0)
	v_mul_f32_e32 v12, v157, v7
	v_pk_fma_f32 v[4:5], v[4:5], v[6:7], v[12:13] op_sel_hi:[1,1,0]
	v_pk_mul_f32 v[2:3], v[2:3], v[6:7]
	v_add_co_u32_e32 v12, vcc, s0, v88
	v_cvt_pk_bf16_f32 v5, v4, v2
	ds_read_b64 v[6:7], v125 offset:11776
	global_store_dword v[8:9], v5, off offset:2048
	v_mov_b32_e32 v5, v158
	v_addc_co_u32_e32 v13, vcc, 0, v89, vcc
	s_waitcnt lgkmcnt(0)
	v_mul_f32_e32 v8, v158, v7
	v_pk_fma_f32 v[4:5], v[4:5], v[6:7], v[8:9] op_sel_hi:[1,1,0]
	v_pk_mul_f32 v[2:3], v[2:3], v[6:7]
	s_mov_b32 s0, 0x21000
	v_cvt_pk_bf16_f32 v5, v4, v2
	ds_read_b64 v[6:7], v125 offset:12288
	global_store_dword v[12:13], v5, off
	v_mov_b32_e32 v5, v87
	v_add_co_u32_e32 v98, vcc, s0, v90
	s_waitcnt lgkmcnt(0)
	v_mul_f32_e32 v8, v87, v7
	v_pk_mul_f32 v[2:3], v[2:3], v[6:7]
	v_pk_fma_f32 v[4:5], v[4:5], v[6:7], v[8:9] op_sel_hi:[1,1,0]
	v_addc_co_u32_e32 v99, vcc, 0, v91, vcc
	v_cvt_pk_bf16_f32 v3, v4, v2
	global_store_dword v[12:13], v3, off offset:2048
	v_mov_b32_e32 v3, v4
	s_waitcnt lgkmcnt(0)
	global_store_dwordx2 v[10:11], v[2:3], off
	global_load_dwordx4 v[2:5], v[98:99], off offset:-4096
	v_mul_f32_e32 v6, 0xbfb8aa3b, v86
	s_mov_b32 s0, 0x23000
	v_exp_f32_e32 v84, v6
	v_add_co_u32_e32 v122, vcc, s0, v90
	s_mov_b64 s[0:1], 0x20000
	s_nop 0
	v_addc_co_u32_e32 v123, vcc, 0, v91, vcc
	global_load_dwordx4 v[6:9], v[122:123], off offset:-4096
	global_load_dwordx4 v[106:109], v[98:99], off offset:96
	v_lshl_add_u64 v[26:27], v[90:91], 0, s[0:1]
	s_mov_b32 s0, 0x22000
	v_add_f32_e32 v216, 1.0, v163
	v_add_f32_e32 v217, -1.0, v216
	v_log_f32_e32 v218, v216
	v_rcp_f32_e32 v219, v217
	v_cmp_eq_f32_e32 vcc, 0, v217
	v_mul_f32_e32 v218, v218, v163
	v_mul_f32_e32 v218, 0x3f317218, v218
	v_mul_f32_e32 v218, v218, v219
	v_cndmask_b32_e32 v100, v218, v163, vcc
	v_add_co_u32_e32 v30, vcc, s0, v90
	s_nop 1
	v_addc_co_u32_e32 v31, vcc, 0, v91, vcc
	global_load_dwordx4 v[10:13], v[26:27], off offset:32
	global_load_dwordx4 v[18:21], v[26:27], off offset:64
	global_load_dwordx4 v[14:17], v[30:31], off offset:32
	global_load_dwordx4 v[22:25], v[30:31], off offset:64
	global_load_dwordx4 v[26:29], v[26:27], off offset:96
	global_load_dwordx4 v[30:33], v[30:31], off offset:96
	global_load_dwordx4 v[90:93], v[98:99], off
	global_load_dwordx4 v[94:97], v[122:123], off
	s_waitcnt vmcnt(10)
	v_mfma_f32_32x32x16_bf16 v[34:49], v[70:73], v[2:5], 0
	global_load_dwordx4 v[102:105], v[98:99], off offset:32
	global_load_dwordx4 v[114:117], v[98:99], off offset:64
	global_load_dwordx4 v[110:113], v[122:123], off offset:32
	global_load_dwordx4 v[118:121], v[122:123], off offset:64
	global_load_dwordx4 v[164:167], v[122:123], off offset:96
	s_waitcnt vmcnt(14)
	v_mfma_f32_32x32x16_bf16 v[50:65], v[70:73], v[6:9], 0
	s_waitcnt vmcnt(12)
	v_mfma_f32_32x32x16_bf16 v[34:49], v[66:69], v[10:13], v[34:49]
	s_waitcnt vmcnt(10)
	v_mfma_f32_32x32x16_bf16 v[50:65], v[66:69], v[14:17], v[50:65]
	s_mov_b32 s0, 0x13f0f000
	v_mfma_f32_32x32x16_bf16 v[34:49], v[78:81], v[18:21], v[34:49]
	s_waitcnt vmcnt(9)
	v_mfma_f32_32x32x16_bf16 v[50:65], v[78:81], v[22:25], v[50:65]
	s_nop 0
	s_waitcnt vmcnt(8)
	v_mfma_f32_32x32x16_bf16 v[34:49], v[74:77], v[26:29], v[34:49]
	s_waitcnt vmcnt(7)
	v_mfma_f32_32x32x16_bf16 v[50:65], v[74:77], v[30:33], v[50:65]
	s_waitcnt vmcnt(6)
	v_mfma_f32_32x32x16_bf16 v[2:17], v[70:73], v[90:93], 0
	s_waitcnt vmcnt(5)
	v_mfma_f32_32x32x16_bf16 v[18:33], v[70:73], v[94:97], 0
	v_mul_f32_e32 v86, 0xbfb8aa3b, v159
	s_nop 0
	s_waitcnt vmcnt(4)
	v_mfma_f32_32x32x16_bf16 v[2:17], v[66:69], v[102:105], v[2:17]
	v_add_f32_e32 v216, 1.0, v84
	v_add_f32_e32 v217, -1.0, v216
	v_log_f32_e32 v218, v216
	v_rcp_f32_e32 v219, v217
	v_cmp_eq_f32_e32 vcc, 0, v217
	v_mul_f32_e32 v218, v218, v84
	v_mul_f32_e32 v218, 0x3f317218, v218
	v_mul_f32_e32 v218, v218, v219
	v_cndmask_b32_e32 v98, v218, v84, vcc
	v_mul_f32_e32 v102, 0xbfb8aa3b, v160
	v_add_co_u32_e32 v96, vcc, s0, v88
	s_mov_b32 s0, 0x13f0e000
	s_nop 0
	v_addc_co_u32_e32 v97, vcc, 0, v89, vcc
	s_waitcnt vmcnt(2)
	v_mfma_f32_32x32x16_bf16 v[18:33], v[66:69], v[110:113], v[18:33]
	v_add_co_u32_e32 v94, vcc, s0, v88
	s_mov_b32 s0, 0x13f0d000
	s_nop 0
	v_addc_co_u32_e32 v95, vcc, 0, v89, vcc
	v_add_co_u32_e32 v92, vcc, s0, v88
	v_mfma_f32_32x32x16_bf16 v[2:17], v[78:81], v[114:117], v[2:17]
	s_nop 0
	v_addc_co_u32_e32 v93, vcc, 0, v89, vcc
	s_mov_b32 s0, 0x13f0c000
	v_add_co_u32_e32 v90, vcc, s0, v88
	s_mov_b32 s0, 0x13f0b000
	s_nop 0
	v_addc_co_u32_e32 v91, vcc, 0, v89, vcc
	s_waitcnt vmcnt(1)
	v_mfma_f32_32x32x16_bf16 v[18:33], v[78:81], v[118:121], v[18:33]
	v_mul_f32_e32 v80, 0xbfb8aa3b, v161
	v_mul_f32_e32 v81, 0xbfb8aa3b, v162
	v_fmamk_f32 v34, v34, 0xbfb8aa3b, v80
	v_exp_f32_e32 v78, v34
	v_fmamk_f32 v34, v50, 0xbfb8aa3b, v81
	v_exp_f32_e32 v79, v34
	v_fmamk_f32 v36, v36, 0xbfb8aa3b, v80
	v_exp_f32_e32 v50, v36
	v_fmamk_f32 v36, v52, 0xbfb8aa3b, v81
	v_pk_add_f32 v[78:79], v[78:79], 1.0 op_sel_hi:[1,0]
	v_mfma_f32_32x32x16_bf16 v[2:17], v[74:77], v[106:109], v[2:17]
	v_mul_f32_e32 v34, v78, v79
	v_rcp_f32_e32 v84, v34
	v_fmamk_f32 v34, v35, 0xbfb8aa3b, v80
	v_fmamk_f32 v35, v51, 0xbfb8aa3b, v81
	v_exp_f32_e32 v34, v34
	v_exp_f32_e32 v35, v35
	v_exp_f32_e32 v51, v36
	v_mul_f32_e32 v79, v79, v84
	v_mul_f32_e32 v78, v78, v84
	v_pk_add_f32 v[34:35], v[34:35], 1.0 op_sel_hi:[1,0]
	v_pk_add_f32 v[50:51], v[50:51], 1.0 op_sel_hi:[1,0]
	v_mul_f32_e32 v36, v34, v35
	v_rcp_f32_e32 v36, v36
	v_mul_f32_e32 v52, v50, v51
	v_rcp_f32_e32 v52, v52
	s_waitcnt vmcnt(0)
; template <int DIR, int MODE> ...
;     ...
;     for (int nt = 0; nt < 2; ++nt) {
;         const float nba = prm[DIR][nt][0], nbx = prm[DIR][nt][1], k8l = prm[DIR][nt][2];
; #pragma unroll
;         for (int i = 0; i < 16; ++i) {
;             const float d1 = 1.f + __builtin_amdgcn_exp2f(__builtin_fmaf(accR[nt][i], -1.4426950408889634f, nba));
;             const float d2 = 1.f + __builtin_amdgcn_exp2f(__builtin_fmaf(accI[nt][i], -1.4426950408889634f, nbx));
;             const float inv = __builtin_amdgcn_rcpf(d1 * d2), rr = inv * d2, ii = inv * d1;
;             const float av = __builtin_amdgcn_exp2f(k8l * rr);
;             accR[nt][i] = av; accI[nt][i] = __builtin_amdgcn_sqrtf(fmaxf(__builtin_fmaf(-av, av, 1.f), 0.f)) * ii; }
	v_mfma_f32_32x32x16_bf16 v[18:33], v[74:77], v[164:167], v[18:33]
	v_mul_f32_e32 v84, v35, v36
	v_mul_f32_e32 v99, v34, v36
	v_fmamk_f32 v34, v37, 0xbfb8aa3b, v80
	v_fmamk_f32 v35, v53, 0xbfb8aa3b, v81
	v_exp_f32_e32 v34, v34
	v_exp_f32_e32 v35, v35
	v_fmamk_f32 v36, v38, 0xbfb8aa3b, v80
	v_fmamk_f32 v37, v54, 0xbfb8aa3b, v81
	v_exp_f32_e32 v36, v36
	v_exp_f32_e32 v37, v37
	v_pk_add_f32 v[34:35], v[34:35], 1.0 op_sel_hi:[1,0]
	v_mul_f32_e32 v51, v51, v52
	v_mul_f32_e32 v38, v34, v35
	v_rcp_f32_e32 v38, v38
	v_pk_add_f32 v[36:37], v[36:37], 1.0 op_sel_hi:[1,0]
	v_mul_f32_e32 v50, v50, v52
	v_mul_f32_e32 v53, v36, v37
	v_rcp_f32_e32 v53, v53
	v_mul_f32_e32 v52, v35, v38
	v_mul_f32_e32 v54, v34, v38
	v_fmamk_f32 v34, v39, 0xbfb8aa3b, v80
	v_fmamk_f32 v35, v55, 0xbfb8aa3b, v81
	v_exp_f32_e32 v34, v34
	v_exp_f32_e32 v35, v35
	v_mul_f32_e32 v103, v37, v53
	v_fmamk_f32 v37, v40, 0xbfb8aa3b, v80
	v_exp_f32_e32 v38, v37
	v_fmamk_f32 v37, v56, 0xbfb8aa3b, v81
	v_pk_add_f32 v[34:35], v[34:35], 1.0 op_sel_hi:[1,0]
	v_exp_f32_e32 v39, v37
	v_mul_f32_e32 v37, v34, v35
	v_rcp_f32_e32 v37, v37
	v_mul_f32_e32 v53, v36, v53
	v_fmamk_f32 v36, v42, 0xbfb8aa3b, v80
	v_exp_f32_e32 v36, v36
	v_mul_f32_e32 v56, v35, v37
	v_mul_f32_e32 v104, v34, v37
	v_fmamk_f32 v34, v41, 0xbfb8aa3b, v80
	v_fmamk_f32 v35, v57, 0xbfb8aa3b, v81
	v_exp_f32_e32 v34, v34
	v_exp_f32_e32 v35, v35
	v_fmamk_f32 v37, v58, 0xbfb8aa3b, v81
	v_exp_f32_e32 v37, v37
	v_pk_add_f32 v[38:39], v[38:39], 1.0 op_sel_hi:[1,0]
	v_fmamk_f32 v44, v44, 0xbfb8aa3b, v80
	v_mul_f32_e32 v40, v38, v39
	v_rcp_f32_e32 v55, v40
	v_pk_add_f32 v[40:41], v[34:35], 1.0 op_sel_hi:[1,0]
	v_pk_add_f32 v[74:75], v[36:37], 1.0 op_sel_hi:[1,0]
	v_mul_f32_e32 v34, v40, v41
	v_rcp_f32_e32 v35, v34
	v_mul_f32_e32 v34, v74, v75
	v_rcp_f32_e32 v193, v34
	v_mov_b32_e32 v101, v75
	v_mul_f32_e32 v105, v39, v55
	v_mul_f32_e32 v57, v40, v35
	v_pk_mul_f32 v[76:77], v[100:101], v[192:193]
	v_mul_f32_e32 v42, v38, v55
	v_mul_f32_e32 v39, v76, v52
	v_exp_f32_e32 v40, v39
	v_mul_f32_e32 v38, v76, v51
	v_exp_f32_e32 v38, v38
	v_mul_f32_e32 v55, v41, v35
	v_fma_f32 v41, -v40, v40, 1.0
	v_max_f32_e32 v41, 0, v41
	v_mul_f32_e32 v51, v76, v56
	v_fma_f32 v39, -v38, v38, 1.0
	v_sqrt_f32_e32 v41, v41
	v_exp_f32_e32 v52, v51
	v_max_f32_e32 v39, 0, v39
	v_sqrt_f32_e32 v39, v39
	v_mul_f32_e32 v41, v54, v41
	v_fma_f32 v54, -v52, v52, 1.0
	v_max_f32_e32 v56, 0, v54
	v_mul_f32_e32 v54, v76, v105
	v_mul_f32_e32 v39, v50, v39
	v_mul_f32_e32 v50, v76, v103
	v_exp_f32_e32 v54, v54
	v_exp_f32_e32 v50, v50
	v_mul_f32_e32 v55, v76, v55
	v_sqrt_f32_e32 v58, v56
	v_exp_f32_e32 v56, v55
	v_fma_f32 v55, -v54, v54, 1.0
	v_fma_f32 v51, -v50, v50, 1.0
	v_max_f32_e32 v55, 0, v55
	v_max_f32_e32 v51, 0, v51
	v_sqrt_f32_e32 v55, v55
	v_sqrt_f32_e32 v51, v51
	v_fma_f32 v75, -v56, v56, 1.0
	v_max_f32_e32 v75, 0, v75
	v_mul_f32_e32 v55, v42, v55
	v_fmamk_f32 v42, v43, 0xbfb8aa3b, v80
	v_mul_f32_e32 v51, v53, v51
	v_mul_f32_e32 v53, v104, v58
	v_exp_f32_e32 v58, v42
	v_fmamk_f32 v42, v59, 0xbfb8aa3b, v81
	v_mul_f32_e32 v34, v76, v79
	v_sqrt_f32_e32 v75, v75
	v_exp_f32_e32 v59, v42
	v_exp_f32_e32 v34, v34
	v_mul_f32_e32 v42, v76, v77
	v_mul_f32_e32 v35, v76, v84
	v_mul_f32_e32 v57, v57, v75
	v_mul_f32_e32 v43, v74, v193
	v_exp_f32_e32 v42, v42
	v_pk_add_f32 v[74:75], v[58:59], 1.0 op_sel_hi:[1,0]
	v_exp_f32_e32 v36, v35
	v_fma_f32 v35, -v34, v34, 1.0
	v_mul_f32_e32 v58, v74, v75
	v_max_f32_e32 v35, 0, v35
	v_rcp_f32_e32 v59, v58
	v_sqrt_f32_e32 v35, v35
	v_fma_f32 v58, -v42, v42, 1.0
	v_max_f32_e32 v58, 0, v58
	v_sqrt_f32_e32 v77, v58
	v_mul_f32_e32 v58, v75, v59
	v_mul_f32_e32 v35, v78, v35
	v_mul_f32_e32 v58, v76, v58
	v_exp_f32_e32 v78, v44
	v_fmamk_f32 v44, v60, 0xbfb8aa3b, v81
	v_exp_f32_e32 v58, v58
	v_exp_f32_e32 v79, v44
	v_fmamk_f32 v45, v45, 0xbfb8aa3b, v80
	v_mul_f32_e32 v59, v74, v59
	v_fma_f32 v44, -v58, v58, 1.0
	v_pk_add_f32 v[78:79], v[78:79], 1.0 op_sel_hi:[1,0]
	v_max_f32_e32 v44, 0, v44
	v_mul_f32_e32 v60, v78, v79
	v_sqrt_f32_e32 v44, v44
	v_rcp_f32_e32 v75, v60
	v_exp_f32_e32 v60, v45
	v_fmamk_f32 v45, v61, 0xbfb8aa3b, v81
	v_exp_f32_e32 v61, v45
	v_mul_f32_e32 v59, v59, v44
	v_mul_f32_e32 v44, v79, v75
	v_mul_f32_e32 v44, v76, v44
	v_mul_f32_e32 v45, v78, v75
	v_exp_f32_e32 v44, v44
	v_pk_add_f32 v[74:75], v[60:61], 1.0 op_sel_hi:[1,0]
	v_fmamk_f32 v46, v46, 0xbfb8aa3b, v80
	v_mul_f32_e32 v60, v74, v75
	v_rcp_f32_e32 v61, v60
	v_fma_f32 v60, -v44, v44, 1.0
	v_max_f32_e32 v60, 0, v60
	v_mul_f32_e32 v43, v43, v77
	v_sqrt_f32_e32 v77, v60
	v_mul_f32_e32 v60, v75, v61
	v_exp_f32_e32 v78, v46
	v_fmamk_f32 v46, v62, 0xbfb8aa3b, v81
	v_mul_f32_e32 v60, v76, v60
	v_exp_f32_e32 v79, v46
	v_exp_f32_e32 v60, v60
	v_fmamk_f32 v47, v47, 0xbfb8aa3b, v80
	v_mul_f32_e32 v61, v74, v61
	v_pk_add_f32 v[78:79], v[78:79], 1.0 op_sel_hi:[1,0]
	v_fma_f32 v46, -v60, v60, 1.0
	v_mul_f32_e32 v62, v78, v79
	v_max_f32_e32 v46, 0, v46
	v_rcp_f32_e32 v75, v62
	v_exp_f32_e32 v62, v47
	v_fmamk_f32 v47, v63, 0xbfb8aa3b, v81
	v_sqrt_f32_e32 v46, v46
	v_exp_f32_e32 v63, v47
	v_mul_f32_e32 v47, v78, v75
	v_mul_f32_e32 v45, v45, v77
	v_mul_f32_e32 v61, v61, v46
	v_mul_f32_e32 v46, v79, v75
	v_pk_add_f32 v[62:63], v[62:63], 1.0 op_sel_hi:[1,0]
	v_mul_f32_e32 v46, v76, v46
	v_mul_f32_e32 v74, v62, v63
	v_exp_f32_e32 v46, v46
	v_rcp_f32_e32 v75, v74
	v_fmamk_f32 v48, v48, 0xbfb8aa3b, v80
	v_exp_f32_e32 v78, v48
	v_fma_f32 v74, -v46, v46, 1.0
	v_mul_f32_e32 v63, v63, v75
	v_max_f32_e32 v74, 0, v74
	v_mul_f32_e32 v63, v76, v63
	v_sqrt_f32_e32 v77, v74
	v_exp_f32_e32 v74, v63
	v_fmamk_f32 v48, v64, 0xbfb8aa3b, v81
	v_exp_f32_e32 v79, v48
	v_mul_f32_e32 v62, v62, v75
	v_fma_f32 v48, -v74, v74, 1.0
; template <int DIR, int MODE> ...
;     ...
;     for (int nt = 0; nt < 2; ++nt) {
;         const float nba = prm[DIR][nt][0], nbx = prm[DIR][nt][1], k8l = prm[DIR][nt][2];
; #pragma unroll
;         for (int i = 0; i < 16; ++i) {
;             const float d1 = 1.f + __builtin_amdgcn_exp2f(__builtin_fmaf(accR[nt][i], -1.4426950408889634f, nba));
;             const float d2 = 1.f + __builtin_amdgcn_exp2f(__builtin_fmaf(accI[nt][i], -1.4426950408889634f, nbx));
;             const float inv = __builtin_amdgcn_rcpf(d1 * d2), rr = inv * d2, ii = inv * d1;
;             const float av = __builtin_amdgcn_exp2f(k8l * rr);
;             accR[nt][i] = av; accI[nt][i] = __builtin_amdgcn_sqrtf(fmaxf(__builtin_fmaf(-av, av, 1.f), 0.f)) * ii; }
	v_max_f32_e32 v48, 0, v48
	v_sqrt_f32_e32 v48, v48
	v_pk_add_f32 v[78:79], v[78:79], 1.0 op_sel_hi:[1,0]
	v_fmac_f32_e32 v80, 0xbfb8aa3b, v49
	v_mul_f32_e32 v63, v78, v79
	v_fmac_f32_e32 v81, 0xbfb8aa3b, v65
	v_rcp_f32_e32 v63, v63
	v_mul_f32_e32 v75, v62, v48
	v_exp_f32_e32 v48, v80
	v_exp_f32_e32 v49, v81
	v_mul_f32_e32 v62, v79, v63
	v_mul_f32_e32 v62, v76, v62
	v_exp_f32_e32 v62, v62
	v_pk_add_f32 v[48:49], v[48:49], 1.0 op_sel_hi:[1,0]
	v_mul_f32_e32 v63, v78, v63
	v_mul_f32_e32 v64, v48, v49
	v_rcp_f32_e32 v65, v64
	v_fma_f32 v64, -v62, v62, 1.0
	v_max_f32_e32 v64, 0, v64
	v_sqrt_f32_e32 v78, v64
	v_mul_f32_e32 v49, v49, v65
	v_mul_f32_e32 v49, v76, v49
	v_exp_f32_e32 v64, v49
	v_fmamk_f32 v2, v2, 0xbfb8aa3b, v86
	v_exp_f32_e32 v76, v2
	v_fmamk_f32 v2, v18, 0xbfb8aa3b, v102
	v_mul_f32_e32 v47, v47, v77
	v_exp_f32_e32 v77, v2
	v_fma_f32 v2, -v64, v64, 1.0
	v_max_f32_e32 v2, 0, v2
	v_sqrt_f32_e32 v2, v2
	v_pk_add_f32 v[76:77], v[76:77], 1.0 op_sel_hi:[1,0]
	v_fmamk_f32 v4, v4, 0xbfb8aa3b, v86
	v_mul_f32_e32 v18, v76, v77
	v_rcp_f32_e32 v49, v18
	v_mul_f32_e32 v18, v48, v65
	v_mul_f32_e32 v65, v18, v2
	v_fmamk_f32 v2, v3, 0xbfb8aa3b, v86
	v_fmamk_f32 v3, v19, 0xbfb8aa3b, v102
	v_exp_f32_e32 v2, v2
	v_exp_f32_e32 v3, v3
	v_exp_f32_e32 v18, v4
	v_fmamk_f32 v4, v20, 0xbfb8aa3b, v102
	v_exp_f32_e32 v19, v4
	v_pk_add_f32 v[2:3], v[2:3], 1.0 op_sel_hi:[1,0]
	v_mul_f32_e32 v48, v77, v49
	v_mul_f32_e32 v4, v2, v3
	v_rcp_f32_e32 v4, v4
	v_mul_f32_e32 v49, v76, v49
	v_pk_add_f32 v[18:19], v[18:19], 1.0 op_sel_hi:[1,0]
	v_mul_f32_e32 v63, v63, v78
	v_mul_f32_e32 v76, v3, v4
	v_mul_f32_e32 v77, v2, v4
	v_fmamk_f32 v2, v5, 0xbfb8aa3b, v86
	v_fmamk_f32 v3, v21, 0xbfb8aa3b, v102
	v_exp_f32_e32 v2, v2
	v_exp_f32_e32 v3, v3
	v_fmamk_f32 v4, v6, 0xbfb8aa3b, v86
	v_fmamk_f32 v5, v22, 0xbfb8aa3b, v102
	v_mul_f32_e32 v20, v18, v19
	v_exp_f32_e32 v4, v4
	v_exp_f32_e32 v5, v5
	v_pk_add_f32 v[2:3], v[2:3], 1.0 op_sel_hi:[1,0]
	v_rcp_f32_e32 v20, v20
	v_mul_f32_e32 v6, v2, v3
	v_rcp_f32_e32 v6, v6
	v_pk_add_f32 v[4:5], v[4:5], 1.0 op_sel_hi:[1,0]
	v_mul_f32_e32 v78, v19, v20
	v_mul_f32_e32 v19, v4, v5
	v_rcp_f32_e32 v19, v19
	v_mul_f32_e32 v80, v3, v6
	v_mul_f32_e32 v81, v2, v6
	v_fmamk_f32 v2, v7, 0xbfb8aa3b, v86
	v_fmamk_f32 v3, v23, 0xbfb8aa3b, v102
	v_exp_f32_e32 v2, v2
	v_exp_f32_e32 v3, v3
	v_mul_f32_e32 v84, v5, v19
	v_fmamk_f32 v5, v8, 0xbfb8aa3b, v86
	v_exp_f32_e32 v6, v5
	v_fmamk_f32 v5, v24, 0xbfb8aa3b, v102
	v_pk_add_f32 v[2:3], v[2:3], 1.0 op_sel_hi:[1,0]
	v_exp_f32_e32 v7, v5
	v_mul_f32_e32 v5, v2, v3
	v_rcp_f32_e32 v5, v5
	v_fma_f32 v37, -v36, v36, 1.0
	v_pk_add_f32 v[6:7], v[6:7], 1.0 op_sel_hi:[1,0]
	v_max_f32_e32 v37, 0, v37
	v_mul_f32_e32 v8, v6, v7
	v_mul_f32_e32 v101, v3, v5
	v_mul_f32_e32 v103, v2, v5
	v_fmamk_f32 v2, v10, 0xbfb8aa3b, v86
	v_fmamk_f32 v3, v26, 0xbfb8aa3b, v102
	v_rcp_f32_e32 v8, v8
	v_exp_f32_e32 v2, v2
	v_exp_f32_e32 v3, v3
	v_mul_f32_e32 v100, v4, v19
	v_mul_f32_e32 v104, v7, v8
	v_mul_f32_e32 v105, v6, v8
	v_fmamk_f32 v4, v9, 0xbfb8aa3b, v86
	v_pk_add_f32 v[8:9], v[2:3], 1.0 op_sel_hi:[1,0]
	v_sqrt_f32_e32 v37, v37
	v_mul_f32_e32 v2, v8, v9
	v_rcp_f32_e32 v193, v2
	v_fmamk_f32 v2, v25, 0xbfb8aa3b, v102
	v_exp_f32_e32 v4, v4
	v_exp_f32_e32 v5, v2
	v_mul_f32_e32 v37, v99, v37
	v_mov_b32_e32 v99, v9
	v_mul_f32_e32 v79, v18, v20
	v_pk_mul_f32 v[18:19], v[98:99], v[192:193]
	v_pk_add_f32 v[6:7], v[4:5], 1.0 op_sel_hi:[1,0]
	v_mul_f32_e32 v2, v18, v48
	v_exp_f32_e32 v2, v2
	v_mul_f32_e32 v3, v6, v7
	v_rcp_f32_e32 v3, v3
	v_mul_f32_e32 v9, v18, v19
	v_fma_f32 v4, -v2, v2, 1.0
	v_max_f32_e32 v4, 0, v4
	v_sqrt_f32_e32 v5, v4
	v_mul_f32_e32 v4, v18, v76
	v_mul_f32_e32 v76, v6, v3
	v_fmamk_f32 v6, v11, 0xbfb8aa3b, v86
	v_exp_f32_e32 v10, v6
	v_fmamk_f32 v6, v27, 0xbfb8aa3b, v102
	v_exp_f32_e32 v11, v6
	v_mul_f32_e32 v48, v7, v3
	v_exp_f32_e32 v20, v9
	v_mul_f32_e32 v8, v8, v193
	v_pk_add_f32 v[10:11], v[10:11], 1.0 op_sel_hi:[1,0]
	v_add_co_u32_e32 v72, vcc, s0, v88
	v_mul_f32_e32 v7, v10, v11
	v_rcp_f32_e32 v7, v7
	v_addc_co_u32_e32 v73, vcc, 0, v89, vcc
	s_mov_b32 s0, 0x13f0a000
	v_mul_f32_e32 v9, v11, v7
	v_mul_f32_e32 v9, v18, v9
	v_exp_f32_e32 v22, v9
	v_fma_f32 v9, -v20, v20, 1.0
	v_max_f32_e32 v9, 0, v9
	v_sqrt_f32_e32 v9, v9
	v_fma_f32 v11, -v22, v22, 1.0
	v_max_f32_e32 v11, 0, v11
	v_sqrt_f32_e32 v11, v11
	v_mul_f32_e32 v7, v10, v7
	v_mul_f32_e32 v21, v8, v9
	v_add_co_u32_e32 v70, vcc, s0, v88
	v_mul_f32_e32 v23, v7, v11
	v_fmamk_f32 v7, v12, 0xbfb8aa3b, v86
	v_exp_f32_e32 v8, v7
	v_fmamk_f32 v7, v28, 0xbfb8aa3b, v102
	v_exp_f32_e32 v9, v7
	v_fmamk_f32 v7, v13, 0xbfb8aa3b, v86
	v_exp_f32_e32 v10, v7
	v_fmamk_f32 v7, v29, 0xbfb8aa3b, v102
	v_exp_f32_e32 v11, v7
	v_pk_add_f32 v[8:9], v[8:9], 1.0 op_sel_hi:[1,0]
	v_addc_co_u32_e32 v71, vcc, 0, v89, vcc
	v_mul_f32_e32 v7, v8, v9
	v_rcp_f32_e32 v7, v7
	v_pk_add_f32 v[10:11], v[10:11], 1.0 op_sel_hi:[1,0]
	s_mov_b32 s0, 0x13f09000
	v_mul_f32_e32 v12, v10, v11
	v_rcp_f32_e32 v19, v12
	v_mul_f32_e32 v9, v9, v7
	v_mul_f32_e32 v9, v18, v9
	v_exp_f32_e32 v12, v9
	v_mul_f32_e32 v9, v11, v19
	v_mul_f32_e32 v9, v18, v9
	v_exp_f32_e32 v24, v9
	v_fma_f32 v9, -v12, v12, 1.0
	v_max_f32_e32 v9, 0, v9
	v_sqrt_f32_e32 v9, v9
	v_fma_f32 v11, -v24, v24, 1.0
	v_max_f32_e32 v11, 0, v11
	v_sqrt_f32_e32 v11, v11
	v_mul_f32_e32 v7, v8, v7
	v_mul_f32_e32 v13, v7, v9
	v_mul_f32_e32 v7, v10, v19
	v_mul_f32_e32 v25, v7, v11
	v_fmamk_f32 v7, v14, 0xbfb8aa3b, v86
	v_exp_f32_e32 v8, v7
	v_fmamk_f32 v7, v30, 0xbfb8aa3b, v102
	v_exp_f32_e32 v9, v7
	v_fmamk_f32 v7, v15, 0xbfb8aa3b, v86
	v_exp_f32_e32 v10, v7
	v_fmamk_f32 v7, v31, 0xbfb8aa3b, v102
	v_exp_f32_e32 v11, v7
	v_pk_add_f32 v[8:9], v[8:9], 1.0 op_sel_hi:[1,0]
; __device__ __forceinline__ unsigned cvt_pk_bf16(float lo, float hi) { unsigned r; asm volatile("v_cvt_pk_bf16_f32 %0, %1, %2" : "=v"(r) : "v"(lo), "v"(hi)); return r; }
; #define LAS __attribute__((address_space(3)))
; #define LDS_WAVE_SYNC() asm volatile("s_waitcnt lgkmcnt(0)" ::: "memory")
; template <int DIR, int MODE> ...
;     ...
;     for (int nt = 0; nt < 2; ++nt) {
;         const float nba = prm[DIR][nt][0], nbx = prm[DIR][nt][1], k8l = prm[DIR][nt][2];
; #pragma unroll
;         for (int i = 0; i < 16; ++i) {
;             const float d1 = 1.f + __builtin_amdgcn_exp2f(__builtin_fmaf(accR[nt][i], -1.4426950408889634f, nba));
;             const float d2 = 1.f + __builtin_amdgcn_exp2f(__builtin_fmaf(accI[nt][i], -1.4426950408889634f, nbx));
;             const float inv = __builtin_amdgcn_rcpf(d1 * d2), rr = inv * d2, ii = inv * d1;
;             const float av = __builtin_amdgcn_exp2f(k8l * rr);
;             accR[nt][i] = av; accI[nt][i] = __builtin_amdgcn_sqrtf(fmaxf(__builtin_fmaf(-av, av, 1.f), 0.f)) * ii; }
;     }
;     float hc = 0.f, ap = 1.f;
;     if (MODE == 1) hc = ((const float*)(a.ws + WS_CAR))[(size_t)((b * NCH + ch) * 2 + DIR) * LW + c];
; #pragma unroll
;     for (int hh = 0; hh < 2; ++hh) {
;         const int half = DIR == 0 ? hh : 1 - hh;
; #pragma unroll
;         for (int nt = 0; nt < 2; ++nt)
; #pragma unroll
;             for (int i = 0; i < 8; ++i) { const int tt = 8 * (i >> 2) + 4 * h + (i & 3);
;                 f32x2 v; v.x = accR[nt][8 * half + i]; v.y = accI[nt][8 * half + i];
;                 *(LAS f32x2*)(au + (tt * 64 + nt * 32 + r32) * 2) = v; }
;         LDS_WAVE_SYNC();
; #pragma unroll
;         for (int s = 0; s < 16; ++s) {
;             const int tt = DIR == 0 ? s : 15 - s, t = half * 16 + tt;
;             const f32x2 v = *(const LAS f32x2*)(au + (tt * 64 + lane) * 2);
;             hc = v.x * hc + v.y * xcr[t];
;             if (MODE == 0) { ap *= v.x;
;                 ((unsigned*)(a.ws + WS_HP))[((size_t)DIR * T + (size_t)b * SEQ + ch * 32 + t) * LW + c] = pg8::cvt_pk_bf16(hc, ap); }
;             if (MODE == 1) { if (DIR == 0) hf[t] = hc; else hf[t] = gl[t] * (hf[t] + hc); }
;         }
;         LDS_WAVE_SYNC();
	v_mul_f32_e32 v6, v18, v78
	v_mul_f32_e32 v7, v8, v9
	v_rcp_f32_e32 v7, v7
	v_pk_add_f32 v[10:11], v[10:11], 1.0 op_sel_hi:[1,0]
	v_add_co_u32_e32 v68, vcc, s0, v88
	v_mul_f32_e32 v14, v10, v11
	v_rcp_f32_e32 v19, v14
	v_mul_f32_e32 v9, v9, v7
	v_mul_f32_e32 v9, v18, v9
	v_exp_f32_e32 v14, v9
	v_mul_f32_e32 v9, v11, v19
	v_mul_f32_e32 v9, v18, v9
	v_exp_f32_e32 v26, v9
	v_fma_f32 v9, -v14, v14, 1.0
	v_max_f32_e32 v9, 0, v9
	v_sqrt_f32_e32 v9, v9
	v_fma_f32 v11, -v26, v26, 1.0
	v_max_f32_e32 v11, 0, v11
	v_sqrt_f32_e32 v11, v11
	v_mul_f32_e32 v7, v8, v7
	v_mul_f32_e32 v15, v7, v9
	v_mul_f32_e32 v7, v10, v19
	v_mul_f32_e32 v27, v7, v11
	v_fmamk_f32 v7, v16, 0xbfb8aa3b, v86
	v_exp_f32_e32 v8, v7
	v_fmamk_f32 v7, v32, 0xbfb8aa3b, v102
	v_exp_f32_e32 v9, v7
	v_fmac_f32_e32 v86, 0xbfb8aa3b, v17
	v_fmac_f32_e32 v102, 0xbfb8aa3b, v33
	v_exp_f32_e32 v10, v86
	v_exp_f32_e32 v11, v102
	v_pk_add_f32 v[8:9], v[8:9], 1.0 op_sel_hi:[1,0]
	v_mov_b32_e32 v86, v1
	v_mul_f32_e32 v7, v8, v9
	v_rcp_f32_e32 v7, v7
	v_pk_add_f32 v[10:11], v[10:11], 1.0 op_sel_hi:[1,0]
	v_addc_co_u32_e32 v69, vcc, 0, v89, vcc
	v_mul_f32_e32 v16, v10, v11
	v_rcp_f32_e32 v19, v16
	v_mul_f32_e32 v9, v9, v7
	v_mul_f32_e32 v9, v18, v9
	v_exp_f32_e32 v16, v9
	v_mul_f32_e32 v9, v11, v19
	v_mul_f32_e32 v9, v18, v9
	v_exp_f32_e32 v28, v9
	v_fma_f32 v9, -v16, v16, 1.0
	v_max_f32_e32 v9, 0, v9
	v_sqrt_f32_e32 v9, v9
	v_fma_f32 v11, -v28, v28, 1.0
	v_max_f32_e32 v11, 0, v11
	v_sqrt_f32_e32 v11, v11
	v_mul_f32_e32 v7, v8, v7
	v_mul_f32_e32 v17, v7, v9
	v_mul_f32_e32 v7, v10, v19
	v_mul_f32_e32 v29, v7, v11
	ds_write2_b64 v124, v[42:43], v[20:21] offset0:64 offset1:96
	ds_write2_b64 v124, v[58:59], v[22:23] offset0:128 offset1:160
	ds_write2_b64 v124, v[44:45], v[12:13] offset0:192 offset1:224
	ds_write2_b64 v126, v[60:61], v[24:25] offset1:32
	ds_write2_b64 v127, v[46:47], v[14:15] offset0:64 offset1:96
	ds_write2_b64 v127, v[74:75], v[26:27] offset0:128 offset1:160
	ds_write2_b64 v127, v[62:63], v[16:17] offset0:192 offset1:224
	ds_write2_b64 v128, v[64:65], v[28:29] offset1:32
	s_waitcnt lgkmcnt(0)
	ds_read_b64 v[8:9], v125 offset:12288
	v_mul_f32_e32 v10, v18, v80
	v_exp_f32_e32 v10, v10
	v_mul_f32_e32 v19, v18, v101
	v_exp_f32_e32 v4, v4
	s_waitcnt lgkmcnt(0)
	v_mul_f32_e32 v12, v87, v9
	v_pk_fma_f32 v[12:13], v[86:87], v[8:9], v[12:13] op_sel_hi:[1,1,0]
	v_fma_f32 v17, -v10, v10, 1.0
	v_cvt_pk_bf16_f32 v11, v12, v8
	ds_read_b64 v[14:15], v125 offset:11776
	v_mov_b32_e32 v13, v158
	global_store_dword v[96:97], v11, off offset:2048
	v_exp_f32_e32 v6, v6
	s_mov_b32 s0, 0x13f08000
	s_waitcnt lgkmcnt(0)
	v_mul_f32_e32 v16, v158, v15
	v_pk_fma_f32 v[12:13], v[12:13], v[14:15], v[16:17] op_sel_hi:[1,1,0]
	v_pk_mul_f32 v[8:9], v[8:9], v[14:15]
	v_max_f32_e32 v13, 0, v17
	v_cvt_pk_bf16_f32 v11, v12, v8
	ds_read_b64 v[14:15], v125 offset:11264
	v_sqrt_f32_e32 v17, v13
	v_mov_b32_e32 v13, v157
	global_store_dword v[96:97], v11, off
	v_mul_f32_e32 v3, v49, v5
	s_waitcnt lgkmcnt(0)
	v_mul_f32_e32 v16, v157, v15
	v_pk_fma_f32 v[12:13], v[12:13], v[14:15], v[16:17] op_sel_hi:[1,1,0]
	v_pk_mul_f32 v[8:9], v[8:9], v[14:15]
	v_fma_f32 v5, -v4, v4, 1.0
	v_cvt_pk_bf16_f32 v13, v12, v8
	ds_read_b64 v[14:15], v125 offset:10752
	global_store_dword v[94:95], v13, off offset:2048
	v_mov_b32_e32 v13, v156
	v_fma_f32 v49, -v6, v6, 1.0
	v_mul_f32_e32 v11, v81, v17
	s_waitcnt lgkmcnt(0)
	v_mul_f32_e32 v16, v156, v15
	v_pk_fma_f32 v[12:13], v[12:13], v[14:15], v[16:17] op_sel_hi:[1,1,0]
	v_pk_mul_f32 v[8:9], v[8:9], v[14:15]
	v_mul_f32_e32 v16, v18, v84
	v_cvt_pk_bf16_f32 v13, v12, v8
	ds_read_b64 v[14:15], v125 offset:10240
	global_store_dword v[94:95], v13, off
	v_mov_b32_e32 v13, v155
	v_exp_f32_e32 v16, v16
	v_add_co_u32_e32 v66, vcc, s0, v88
	s_waitcnt lgkmcnt(0)
	v_mul_f32_e32 v20, v155, v15
	v_pk_fma_f32 v[12:13], v[12:13], v[14:15], v[20:21] op_sel_hi:[1,1,0]
	v_pk_mul_f32 v[8:9], v[8:9], v[14:15]
	v_fma_f32 v17, -v16, v16, 1.0
	v_cvt_pk_bf16_f32 v13, v12, v8
	ds_read_b64 v[14:15], v125 offset:9728
	global_store_dword v[92:93], v13, off offset:2048
	v_mov_b32_e32 v13, v154
	v_max_f32_e32 v5, 0, v5
	v_max_f32_e32 v7, 0, v49
	s_waitcnt lgkmcnt(0)
	v_mul_f32_e32 v20, v154, v15
	v_pk_fma_f32 v[12:13], v[12:13], v[14:15], v[20:21] op_sel_hi:[1,1,0]
	v_pk_mul_f32 v[8:9], v[8:9], v[14:15]
	v_exp_f32_e32 v20, v19
	v_cvt_pk_bf16_f32 v13, v12, v8
	ds_read_b64 v[14:15], v125 offset:9216
	global_store_dword v[92:93], v13, off
	v_mov_b32_e32 v13, v153
	v_fma_f32 v19, -v20, v20, 1.0
	v_max_f32_e32 v19, 0, v19
	s_waitcnt lgkmcnt(0)
	v_mul_f32_e32 v22, v153, v15
	v_pk_fma_f32 v[12:13], v[12:13], v[14:15], v[22:23] op_sel_hi:[1,1,0]
	v_pk_mul_f32 v[8:9], v[8:9], v[14:15]
	v_sqrt_f32_e32 v19, v19
	v_cvt_pk_bf16_f32 v13, v12, v8
	ds_read_b64 v[14:15], v125 offset:8704
	global_store_dword v[90:91], v13, off offset:2048
	v_mov_b32_e32 v13, v152
	v_mul_f32_e32 v21, v103, v19
	v_mul_f32_e32 v19, v18, v104
	s_waitcnt lgkmcnt(0)
	v_mul_f32_e32 v22, v152, v15
	v_pk_fma_f32 v[12:13], v[12:13], v[14:15], v[22:23] op_sel_hi:[1,1,0]
	v_pk_mul_f32 v[8:9], v[8:9], v[14:15]
	v_mul_f32_e32 v18, v18, v48
	v_cvt_pk_bf16_f32 v13, v12, v8
	ds_read_b64 v[14:15], v125 offset:8192
	global_store_dword v[90:91], v13, off
	v_mov_b32_e32 v13, v151
	v_exp_f32_e32 v18, v18
	v_max_f32_e32 v17, 0, v17
	s_waitcnt lgkmcnt(0)
	v_mul_f32_e32 v22, v151, v15
	v_pk_fma_f32 v[12:13], v[12:13], v[14:15], v[22:23] op_sel_hi:[1,1,0]
	v_pk_mul_f32 v[8:9], v[8:9], v[14:15]
	v_addc_co_u32_e32 v67, vcc, 0, v89, vcc
	v_cvt_pk_bf16_f32 v13, v12, v8
	ds_read_b64 v[14:15], v125 offset:7680
	global_store_dword v[72:73], v13, off offset:2048
	v_mov_b32_e32 v13, v150
	v_sqrt_f32_e32 v5, v5
	v_sqrt_f32_e32 v7, v7
	s_waitcnt lgkmcnt(0)
; __device__ __forceinline__ unsigned cvt_pk_bf16(float lo, float hi) { unsigned r; asm volatile("v_cvt_pk_bf16_f32 %0, %1, %2" : "=v"(r) : "v"(lo), "v"(hi)); return r; }
; #define LAS __attribute__((address_space(3)))
; #define LDS_WAVE_SYNC() asm volatile("s_waitcnt lgkmcnt(0)" ::: "memory")
; template <int DIR, int MODE> ...
;     ...
;     for (int hh = 0; hh < 2; ++hh) {
;         const int half = DIR == 0 ? hh : 1 - hh;
; #pragma unroll
;         for (int nt = 0; nt < 2; ++nt)
; #pragma unroll
;             for (int i = 0; i < 8; ++i) { const int tt = 8 * (i >> 2) + 4 * h + (i & 3);
;                 f32x2 v; v.x = accR[nt][8 * half + i]; v.y = accI[nt][8 * half + i];
;                 *(LAS f32x2*)(au + (tt * 64 + nt * 32 + r32) * 2) = v; }
;         LDS_WAVE_SYNC();
; #pragma unroll
;         for (int s = 0; s < 16; ++s) {
;             const int tt = DIR == 0 ? s : 15 - s, t = half * 16 + tt;
;             const f32x2 v = *(const LAS f32x2*)(au + (tt * 64 + lane) * 2);
;             hc = v.x * hc + v.y * xcr[t];
;             if (MODE == 0) { ap *= v.x;
;                 ((unsigned*)(a.ws + WS_HP))[((size_t)DIR * T + (size_t)b * SEQ + ch * 32 + t) * LW + c] = pg8::cvt_pk_bf16(hc, ap); }
;             if (MODE == 1) { if (DIR == 0) hf[t] = hc; else hf[t] = gl[t] * (hf[t] + hc); }
;         }
;         LDS_WAVE_SYNC();
	v_mul_f32_e32 v22, v150, v15
	v_pk_fma_f32 v[12:13], v[12:13], v[14:15], v[22:23] op_sel_hi:[1,1,0]
	v_pk_mul_f32 v[8:9], v[8:9], v[14:15]
	v_fma_f32 v23, -v18, v18, 1.0
	v_cvt_pk_bf16_f32 v13, v12, v8
	ds_read_b64 v[14:15], v125 offset:7168
	global_store_dword v[72:73], v13, off
	v_mov_b32_e32 v13, v149
	v_max_f32_e32 v23, 0, v23
	v_exp_f32_e32 v22, v19
	s_waitcnt lgkmcnt(0)
	v_mul_f32_e32 v24, v149, v15
	v_pk_fma_f32 v[12:13], v[12:13], v[14:15], v[24:25] op_sel_hi:[1,1,0]
	v_pk_mul_f32 v[8:9], v[8:9], v[14:15]
	v_fma_f32 v19, -v22, v22, 1.0
	v_cvt_pk_bf16_f32 v13, v12, v8
	ds_read_b64 v[14:15], v125 offset:6656
	global_store_dword v[70:71], v13, off offset:2048
	v_mov_b32_e32 v13, v148
	v_max_f32_e32 v19, 0, v19
	v_sqrt_f32_e32 v17, v17
	s_waitcnt lgkmcnt(0)
	v_mul_f32_e32 v24, v148, v15
	v_pk_fma_f32 v[12:13], v[12:13], v[14:15], v[24:25] op_sel_hi:[1,1,0]
	v_pk_mul_f32 v[8:9], v[8:9], v[14:15]
	v_sqrt_f32_e32 v19, v19
	v_cvt_pk_bf16_f32 v13, v12, v8
	ds_read_b64 v[14:15], v125 offset:6144
	global_store_dword v[70:71], v13, off
	v_mov_b32_e32 v13, v147
	v_mul_f32_e32 v5, v77, v5
	v_mul_f32_e32 v7, v79, v7
	s_waitcnt lgkmcnt(0)
	v_mul_f32_e32 v24, v147, v15
	v_pk_fma_f32 v[12:13], v[12:13], v[14:15], v[24:25] op_sel_hi:[1,1,0]
	v_pk_mul_f32 v[8:9], v[8:9], v[14:15]
	v_mul_f32_e32 v17, v100, v17
	v_cvt_pk_bf16_f32 v13, v12, v8
	ds_read_b64 v[14:15], v125 offset:5632
	global_store_dword v[68:69], v13, off offset:2048
	v_mov_b32_e32 v13, v146
	s_mov_b32 s0, 0x13f07000
	s_waitcnt lgkmcnt(0)
	v_mul_f32_e32 v24, v146, v15
	v_pk_fma_f32 v[12:13], v[12:13], v[14:15], v[24:25] op_sel_hi:[1,1,0]
	v_pk_mul_f32 v[8:9], v[8:9], v[14:15]
	v_sqrt_f32_e32 v25, v23
	v_cvt_pk_bf16_f32 v13, v12, v8
	ds_read_b64 v[14:15], v125 offset:5120
	global_store_dword v[68:69], v13, off
	v_mov_b32_e32 v13, v145
	v_mul_f32_e32 v23, v105, v19
	v_mul_f32_e32 v19, v76, v25
	s_waitcnt lgkmcnt(0)
	v_mul_f32_e32 v24, v145, v15
	v_pk_fma_f32 v[12:13], v[12:13], v[14:15], v[24:25] op_sel_hi:[1,1,0]
	v_pk_mul_f32 v[8:9], v[8:9], v[14:15]
	s_nop 0
	v_cvt_pk_bf16_f32 v13, v12, v8
	ds_read_b64 v[14:15], v125 offset:4608
	global_store_dword v[66:67], v13, off offset:2048
	v_mov_b32_e32 v13, v144
	s_waitcnt lgkmcnt(0)
	v_mul_f32_e32 v24, v144, v15
	v_pk_fma_f32 v[12:13], v[12:13], v[14:15], v[24:25] op_sel_hi:[1,1,0]
	v_pk_mul_f32 v[8:9], v[8:9], v[14:15]
	s_nop 0
	v_cvt_pk_bf16_f32 v13, v12, v8
	global_store_dword v[66:67], v13, off
	s_waitcnt lgkmcnt(0)
	ds_write2_b64 v124, v[34:35], v[2:3] offset0:64 offset1:96
	ds_write2_b64 v124, v[36:37], v[4:5] offset0:128 offset1:160
	ds_write2_b64 v124, v[38:39], v[6:7] offset0:192 offset1:224
	ds_write2_b64 v126, v[40:41], v[10:11] offset1:32
	ds_write2_b64 v127, v[50:51], v[16:17] offset0:64 offset1:96
	ds_write2_b64 v127, v[52:53], v[20:21] offset0:128 offset1:160
	ds_write2_b64 v127, v[54:55], v[22:23] offset0:192 offset1:224
	ds_write2_b64 v128, v[56:57], v[18:19] offset1:32
	s_waitcnt lgkmcnt(0)
	ds_read_b64 v[2:3], v125 offset:12288
	v_mov_b32_e32 v13, v143
	s_waitcnt lgkmcnt(0)
	v_mul_f32_e32 v4, v143, v3
	v_pk_fma_f32 v[4:5], v[12:13], v[2:3], v[4:5] op_sel_hi:[1,1,0]
	v_pk_mul_f32 v[2:3], v[8:9], v[2:3]
	v_add_co_u32_e32 v8, vcc, s0, v88
	v_cvt_pk_bf16_f32 v5, v4, v2
	ds_read_b64 v[6:7], v125 offset:11776
	s_nop 0
	v_addc_co_u32_e32 v9, vcc, 0, v89, vcc
	global_store_dword v[8:9], v5, off offset:2048
	v_mov_b32_e32 v5, v142
	s_waitcnt lgkmcnt(0)
	v_mul_f32_e32 v10, v142, v7
	v_pk_fma_f32 v[4:5], v[4:5], v[6:7], v[10:11] op_sel_hi:[1,1,0]
	v_pk_mul_f32 v[2:3], v[2:3], v[6:7]
	s_mov_b32 s0, 0x13f06000
	v_cvt_pk_bf16_f32 v5, v4, v2
	ds_read_b64 v[6:7], v125 offset:11264
	global_store_dword v[8:9], v5, off
	v_mov_b32_e32 v5, v141
	v_lshl_add_u64 v[12:13], s[40:41], 0, v[82:83]
	s_waitcnt lgkmcnt(0)
	v_mul_f32_e32 v8, v141, v7
	v_pk_fma_f32 v[4:5], v[4:5], v[6:7], v[8:9] op_sel_hi:[1,1,0]
	v_pk_mul_f32 v[2:3], v[2:3], v[6:7]
	v_add_co_u32_e32 v8, vcc, s0, v88
	v_cvt_pk_bf16_f32 v5, v4, v2
	ds_read_b64 v[6:7], v125 offset:10752
	s_nop 0
	v_addc_co_u32_e32 v9, vcc, 0, v89, vcc
	global_store_dword v[8:9], v5, off offset:2048
	v_mov_b32_e32 v5, v140
	s_waitcnt lgkmcnt(0)
	v_mul_f32_e32 v10, v140, v7
	v_pk_fma_f32 v[4:5], v[4:5], v[6:7], v[10:11] op_sel_hi:[1,1,0]
	v_pk_mul_f32 v[2:3], v[2:3], v[6:7]
	s_mov_b32 s0, 0x13f05000
	v_cvt_pk_bf16_f32 v5, v4, v2
	ds_read_b64 v[6:7], v125 offset:10240
	global_store_dword v[8:9], v5, off
	v_mov_b32_e32 v5, v139
	s_waitcnt lgkmcnt(0)
; __device__ __forceinline__ unsigned cvt_pk_bf16(float lo, float hi) { unsigned r; asm volatile("v_cvt_pk_bf16_f32 %0, %1, %2" : "=v"(r) : "v"(lo), "v"(hi)); return r; }
; #define LAS __attribute__((address_space(3)))
; #define LDS_WAVE_SYNC() asm volatile("s_waitcnt lgkmcnt(0)" ::: "memory")
; template <int DIR, int MODE> ...
;     ...
;         for (int s = 0; s < 16; ++s) {
;             const int tt = DIR == 0 ? s : 15 - s, t = half * 16 + tt;
;             const f32x2 v = *(const LAS f32x2*)(au + (tt * 64 + lane) * 2);
;             hc = v.x * hc + v.y * xcr[t];
;             if (MODE == 0) { ap *= v.x;
;                 ((unsigned*)(a.ws + WS_HP))[((size_t)DIR * T + (size_t)b * SEQ + ch * 32 + t) * LW + c] = pg8::cvt_pk_bf16(hc, ap); }
;             if (MODE == 1) { if (DIR == 0) hf[t] = hc; else hf[t] = gl[t] * (hf[t] + hc); }
;         }
;         LDS_WAVE_SYNC();
;     }
;     if (MODE == 0) { f32x2 v; v.x = ap; v.y = hc; ((f32x2*)(a.ws + WS_TOT))[(size_t)((b * NCH + ch) * 2 + DIR) * LW + c] = v; }
	v_mul_f32_e32 v8, v139, v7
	v_pk_fma_f32 v[4:5], v[4:5], v[6:7], v[8:9] op_sel_hi:[1,1,0]
	v_pk_mul_f32 v[2:3], v[2:3], v[6:7]
	v_add_co_u32_e32 v8, vcc, s0, v88
	v_cvt_pk_bf16_f32 v5, v4, v2
	ds_read_b64 v[6:7], v125 offset:9728
	s_nop 0
	v_addc_co_u32_e32 v9, vcc, 0, v89, vcc
	global_store_dword v[8:9], v5, off offset:2048
	v_mov_b32_e32 v5, v138
	s_waitcnt lgkmcnt(0)
	v_mul_f32_e32 v10, v138, v7
	v_pk_fma_f32 v[4:5], v[4:5], v[6:7], v[10:11] op_sel_hi:[1,1,0]
	v_pk_mul_f32 v[2:3], v[2:3], v[6:7]
	s_mov_b32 s0, 0x13f04000
	v_cvt_pk_bf16_f32 v5, v4, v2
	ds_read_b64 v[6:7], v125 offset:9216
	global_store_dword v[8:9], v5, off
	v_mov_b32_e32 v5, v137
	s_waitcnt lgkmcnt(0)
	v_mul_f32_e32 v8, v137, v7
	v_pk_fma_f32 v[4:5], v[4:5], v[6:7], v[8:9] op_sel_hi:[1,1,0]
	v_pk_mul_f32 v[2:3], v[2:3], v[6:7]
	v_add_co_u32_e32 v8, vcc, s0, v88
	v_cvt_pk_bf16_f32 v5, v4, v2
	ds_read_b64 v[6:7], v125 offset:8704
	s_nop 0
	v_addc_co_u32_e32 v9, vcc, 0, v89, vcc
	global_store_dword v[8:9], v5, off offset:2048
	v_mov_b32_e32 v5, v136
	s_waitcnt lgkmcnt(0)
	v_mul_f32_e32 v10, v136, v7
	v_pk_fma_f32 v[4:5], v[4:5], v[6:7], v[10:11] op_sel_hi:[1,1,0]
	v_pk_mul_f32 v[2:3], v[2:3], v[6:7]
	s_mov_b32 s0, 0x13f03000
	v_cvt_pk_bf16_f32 v5, v4, v2
	ds_read_b64 v[6:7], v125 offset:8192
	global_store_dword v[8:9], v5, off
	v_mov_b32_e32 v5, v135
	s_waitcnt lgkmcnt(0)
	v_mul_f32_e32 v8, v135, v7
	v_pk_fma_f32 v[4:5], v[4:5], v[6:7], v[8:9] op_sel_hi:[1,1,0]
	v_pk_mul_f32 v[2:3], v[2:3], v[6:7]
	v_add_co_u32_e32 v8, vcc, s0, v88
	v_cvt_pk_bf16_f32 v5, v4, v2
	ds_read_b64 v[6:7], v125 offset:7680
	s_nop 0
	v_addc_co_u32_e32 v9, vcc, 0, v89, vcc
	global_store_dword v[8:9], v5, off offset:2048
	v_mov_b32_e32 v5, v134
	s_waitcnt lgkmcnt(0)
	v_mul_f32_e32 v10, v134, v7
	v_pk_fma_f32 v[4:5], v[4:5], v[6:7], v[10:11] op_sel_hi:[1,1,0]
	v_pk_mul_f32 v[2:3], v[2:3], v[6:7]
	s_mov_b32 s0, 0x13f02000
	v_cvt_pk_bf16_f32 v5, v4, v2
	ds_read_b64 v[6:7], v125 offset:7168
	global_store_dword v[8:9], v5, off
	v_mov_b32_e32 v5, v133
	s_waitcnt lgkmcnt(0)
	v_mul_f32_e32 v8, v133, v7
	v_pk_fma_f32 v[4:5], v[4:5], v[6:7], v[8:9] op_sel_hi:[1,1,0]
	v_pk_mul_f32 v[2:3], v[2:3], v[6:7]
	v_add_co_u32_e32 v8, vcc, s0, v88
	v_cvt_pk_bf16_f32 v5, v4, v2
	ds_read_b64 v[6:7], v125 offset:6656
	s_nop 0
	v_addc_co_u32_e32 v9, vcc, 0, v89, vcc
	global_store_dword v[8:9], v5, off offset:2048
	v_mov_b32_e32 v5, v132
	s_waitcnt lgkmcnt(0)
	v_mul_f32_e32 v10, v132, v7
	v_pk_fma_f32 v[4:5], v[4:5], v[6:7], v[10:11] op_sel_hi:[1,1,0]
	v_pk_mul_f32 v[2:3], v[2:3], v[6:7]
	s_mov_b32 s0, 0x13f01000
	v_cvt_pk_bf16_f32 v5, v4, v2
	ds_read_b64 v[6:7], v125 offset:6144
	global_store_dword v[8:9], v5, off
	v_mov_b32_e32 v5, v131
	v_add_co_u32_e32 v10, vcc, s0, v88
	s_waitcnt lgkmcnt(0)
	v_mul_f32_e32 v8, v131, v7
	v_pk_fma_f32 v[4:5], v[4:5], v[6:7], v[8:9] op_sel_hi:[1,1,0]
	v_pk_mul_f32 v[2:3], v[2:3], v[6:7]
	v_addc_co_u32_e32 v11, vcc, 0, v89, vcc
	v_cvt_pk_bf16_f32 v5, v4, v2
	ds_read_b64 v[6:7], v125 offset:5632
	global_store_dword v[10:11], v5, off offset:2048
	v_mov_b32_e32 v5, v130
	s_mov_b32 s0, 0x13f00000
	v_add_co_u32_e32 v8, vcc, s0, v88
	s_waitcnt lgkmcnt(0)
	v_mul_f32_e32 v14, v130, v7
	v_pk_fma_f32 v[4:5], v[4:5], v[6:7], v[14:15] op_sel_hi:[1,1,0]
	v_pk_mul_f32 v[2:3], v[2:3], v[6:7]
	v_addc_co_u32_e32 v9, vcc, 0, v89, vcc
	v_cvt_pk_bf16_f32 v5, v4, v2
	ds_read_b64 v[6:7], v125 offset:5120
	global_store_dword v[10:11], v5, off
	v_mov_b32_e32 v5, v0
	v_add_co_u32_e32 v12, vcc, 0x11901000, v12
	s_waitcnt lgkmcnt(0)
	v_mul_f32_e32 v0, v0, v7
	v_pk_fma_f32 v[4:5], v[4:5], v[6:7], v[0:1] op_sel_hi:[1,1,0]
	v_pk_mul_f32 v[2:3], v[2:3], v[6:7]
	v_mov_b32_e32 v5, v85
	v_cvt_pk_bf16_f32 v0, v4, v2
	ds_read_b64 v[6:7], v125 offset:4608
	global_store_dword v[8:9], v0, off offset:2048
	v_addc_co_u32_e32 v13, vcc, 0, v13, vcc
	s_mov_b64 s[0:1], 0
	s_waitcnt lgkmcnt(0)
	v_mul_f32_e32 v0, v85, v7
	v_pk_fma_f32 v[4:5], v[4:5], v[6:7], v[0:1] op_sel_hi:[1,1,0]
	v_pk_mul_f32 v[2:3], v[2:3], v[6:7]
	s_nop 0
	v_cvt_pk_bf16_f32 v0, v4, v2
	global_store_dword v[8:9], v0, off
	s_waitcnt lgkmcnt(0)
	v_mov_b32_e32 v3, v4
	global_store_dwordx2 v[12:13], v[2:3], off
